# P8 small_gemm K loop rewritten with 8 K-steps of global loads in flight
# baseline (speedup 1.0000x reference)
; #define LDSBAR() do { asm volatile("s_waitcnt lgkmcnt(0)" ::: "memory"); __builtin_amdgcn_s_barrier(); asm volatile("" ::: "memory"); } while (0)
;     __device__ __forceinline__ Pre pre4(int row, int col) const { const float* sb = (row < TP) ? srcP : srcS - (size_t)TP * DM; Pre p; p.s = NTL((const f32x4*)(sb + (size_t)row * DM + col)); return p; }
;     __device__ __forceinline__ Pre pre4(int row, int col) const { const size_t o = (size_t)row * DM + col; Pre p; p.g = NTL((const v2u*)(SG + o)); p.m = (v2u){0u, 0u}; if (MODE == 1) p.m = NTL((const v2u*)(MG + o)); return p; }
; #define SG_LOAD(R, s_) do { if ((s_) < ns) { R.a0 = NTL((const GAS v4u*)(ap + (s_) * 128)); R.a1 = NTL((const GAS v4u*)(ap + (s_) * 128 + 64)); R.b0 = NTL((const GAS v4u*)(bp + (s_) * 128)); R.b1 = NTL((const GAS v4u*)(bp + (s_) * 128 + 64)); } } while (0)
; #define SG_STORE(R, b_) do { *(LAS v4u*)(As + (b_) * BUF + prow * LDT + pk) = R.a0; *(LAS v4u*)(As + (b_) * BUF + prow * LDT + pk + 64) = R.a1; *(LAS v4u*)(Bs + (b_) * BUF + prow * LDT + pk) = R.b0; *(LAS v4u*)(Bs + (b_) * BUF + prow * LDT + pk + 64) = R.b1; } while (0)
; template <class Epi>
; __device__ __forceinline__ void small_gemm(const Frame& F, const bf16* A, const bf16* Bt, int row_base, int K, const Epi E) {
;     ...
;         const typename Epi::Pre ep0 = E.pre4(r0 + 16 * (w & 3) + r, c0 + 32 * (w >> 2) + 4 * q), ep1 = E.pre4(r0 + 16 * (w & 3) + r, c0 + 32 * (w >> 2) + 16 + 4 * q);
;     ...
;         SgPre R0, R1, R2, R3;
;         SG_LOAD(R0, 0); SG_LOAD(R1, 1); SG_LOAD(R2, 2);
;         SG_STORE(R0, 0); LDSBAR();
;         for (int s = 0; s < ns; s += 4) {
;             SG_LOAD(R3, s + 3); SG_COMP(0); if (s + 1 < ns) SG_STORE(R1, 1); LDSBAR(); if (s + 1 >= ns) break;
;             SG_LOAD(R0, s + 4); SG_COMP(1); if (s + 2 < ns) SG_STORE(R2, 0); LDSBAR(); if (s + 2 >= ns) break;
;             SG_LOAD(R1, s + 5); SG_COMP(0); if (s + 3 < ns) SG_STORE(R3, 1); LDSBAR(); if (s + 3 >= ns) break;
;             SG_LOAD(R2, s + 6); SG_COMP(1); if (s + 4 < ns) SG_STORE(R0, 0); LDSBAR();
;         }
.LBB0_1876:
	s_and_b32 s15, s8, 0xffffffc0
	s_and_b32 s16, s6, 0x3c0
	s_addk_i32 s15, 0x4000
	v_add_u32_e32 v2, s16, v38
	s_add_i32 s19, s16, s3
	v_add_u32_e32 v3, s15, v38
	v_mad_i64_i32 v[32:33], s[16:17], v2, s12, v[28:29]
	v_mad_i64_i32 v[34:35], s[16:17], v3, s12, v[26:27]
	v_or_b32_e32 v2, s15, v39
	v_ashrrev_i32_e32 v3, 31, v2
	v_or_b32_e32 v4, s19, v40
	v_lshlrev_b64 v[2:3], 12, v[2:3]
	v_ashrrev_i32_e32 v5, 31, v4
	v_lshl_add_u64 v[2:3], s[20:21], 0, v[2:3]
	v_lshl_add_u64 v[30:31], v[4:5], 2, v[2:3]
	global_load_dwordx4 v[6:9], v[30:31], off
	global_load_dwordx4 v[2:5], v[30:31], off offset:64
	s_add_i32 s14, s14, s18
	s_add_i32 s6, s6, s7
	s_add_i32 s8, s8, s9
	s_cmpk_lt_i32 s14, 0x100
	v_add_co_u32_e32 v22, vcc, 0x1000, v34
	s_nop 0
	v_addc_co_u32_e32 v23, vcc, 0, v35, vcc
	v_add_co_u32_e32 v24, vcc, 0x1000, v32
	s_nop 0
	v_addc_co_u32_e32 v25, vcc, 0, v33, vcc
	global_load_dwordx4 v[46:49], v[34:35], off
	global_load_dwordx4 v[50:53], v[34:35], off offset:128
	global_load_dwordx4 v[54:57], v[32:33], off
	global_load_dwordx4 v[58:61], v[32:33], off offset:128
	global_load_dwordx4 v[62:65], v[34:35], off offset:256
	global_load_dwordx4 v[66:69], v[34:35], off offset:384
	global_load_dwordx4 v[70:73], v[32:33], off offset:256
	global_load_dwordx4 v[74:77], v[32:33], off offset:384
	global_load_dwordx4 v[78:81], v[34:35], off offset:512
	global_load_dwordx4 v[82:85], v[34:35], off offset:640
	global_load_dwordx4 v[86:89], v[32:33], off offset:512
	global_load_dwordx4 v[90:93], v[32:33], off offset:640
	global_load_dwordx4 v[94:97], v[34:35], off offset:768
	global_load_dwordx4 v[98:101], v[34:35], off offset:896
	global_load_dwordx4 v[102:105], v[32:33], off offset:768
	global_load_dwordx4 v[106:109], v[32:33], off offset:896
	global_load_dwordx4 v[110:113], v[34:35], off offset:1024
	global_load_dwordx4 v[114:117], v[34:35], off offset:1152
	global_load_dwordx4 v[118:121], v[32:33], off offset:1024
	global_load_dwordx4 v[122:125], v[32:33], off offset:1152
	global_load_dwordx4 v[126:129], v[34:35], off offset:1280
	global_load_dwordx4 v[130:133], v[34:35], off offset:1408
	global_load_dwordx4 v[134:137], v[32:33], off offset:1280
	global_load_dwordx4 v[138:141], v[32:33], off offset:1408
	global_load_dwordx4 v[190:193], v[34:35], off offset:1536
	global_load_dwordx4 v[194:197], v[34:35], off offset:1664
	global_load_dwordx4 v[198:201], v[32:33], off offset:1536
	global_load_dwordx4 v[202:205], v[32:33], off offset:1664
	global_load_dwordx4 v[206:209], v[34:35], off offset:1792
	global_load_dwordx4 v[210:213], v[34:35], off offset:1920
	global_load_dwordx4 v[214:217], v[32:33], off offset:1792
	global_load_dwordx4 v[218:221], v[32:33], off offset:1920
	s_waitcnt vmcnt(28)
	ds_write_b128 v41, v[46:49]
	ds_write_b128 v41, v[50:53] offset:128
	ds_write_b128 v41, v[54:57] offset:34816
	ds_write_b128 v41, v[58:61] offset:34944
	s_waitcnt lgkmcnt(0)
	global_load_dwordx4 v[46:49], v[34:35], off offset:2048
	global_load_dwordx4 v[50:53], v[34:35], off offset:2176
	global_load_dwordx4 v[54:57], v[32:33], off offset:2048
	global_load_dwordx4 v[58:61], v[32:33], off offset:2176
	s_barrier
	ds_read_b128 v[222:225], v42
	ds_read_b128 v[238:241], v43 offset:34816
	ds_read_b128 v[174:177], v43 offset:39168
	ds_read_b128 v[226:229], v42 offset:64
	ds_read_b128 v[142:145], v43 offset:34880
	ds_read_b128 v[178:181], v43 offset:39232
	ds_read_b128 v[230:233], v42 offset:128
	ds_read_b128 v[146:149], v43 offset:34944
	ds_read_b128 v[182:185], v43 offset:39296
	ds_read_b128 v[234:237], v42 offset:192
	ds_read_b128 v[170:173], v43 offset:35008
	ds_read_b128 v[18:21], v43 offset:39360
	s_waitcnt lgkmcnt(9)
	v_mfma_f32_16x16x32_bf16 v[14:17], v[238:241], v[222:225], 0
	v_mfma_f32_16x16x32_bf16 v[10:13], v[174:177], v[222:225], 0
	s_waitcnt lgkmcnt(6)
	v_mfma_f32_16x16x32_bf16 v[14:17], v[142:145], v[226:229], v[14:17]
	v_mfma_f32_16x16x32_bf16 v[10:13], v[178:181], v[226:229], v[10:13]
	s_waitcnt lgkmcnt(3)
	v_mfma_f32_16x16x32_bf16 v[14:17], v[146:149], v[230:233], v[14:17]
	v_mfma_f32_16x16x32_bf16 v[10:13], v[182:185], v[230:233], v[10:13]
	s_waitcnt lgkmcnt(0)
	v_mfma_f32_16x16x32_bf16 v[14:17], v[170:173], v[234:237], v[14:17]
	v_mfma_f32_16x16x32_bf16 v[10:13], v[18:21], v[234:237], v[10:13]
	s_waitcnt vmcnt(28)
	ds_write_b128 v41, v[62:65] offset:17408
	ds_write_b128 v41, v[66:69] offset:17536
	ds_write_b128 v41, v[70:73] offset:52224
	ds_write_b128 v41, v[74:77] offset:52352
	s_waitcnt lgkmcnt(0)
	global_load_dwordx4 v[62:65], v[34:35], off offset:2304
	global_load_dwordx4 v[66:69], v[34:35], off offset:2432
	global_load_dwordx4 v[70:73], v[32:33], off offset:2304
	global_load_dwordx4 v[74:77], v[32:33], off offset:2432
	s_barrier
	ds_read_b128 v[222:225], v42 offset:17408
	ds_read_b128 v[238:241], v43 offset:52224
	ds_read_b128 v[174:177], v43 offset:56576
	ds_read_b128 v[226:229], v42 offset:17472
	ds_read_b128 v[142:145], v43 offset:52288
	ds_read_b128 v[178:181], v43 offset:56640
	ds_read_b128 v[230:233], v42 offset:17536
	ds_read_b128 v[146:149], v43 offset:52352
	ds_read_b128 v[182:185], v43 offset:56704
	ds_read_b128 v[234:237], v42 offset:17600
	ds_read_b128 v[170:173], v43 offset:52416
	ds_read_b128 v[18:21], v43 offset:56768
	s_waitcnt lgkmcnt(9)
	v_mfma_f32_16x16x32_bf16 v[14:17], v[238:241], v[222:225], v[14:17]
	v_mfma_f32_16x16x32_bf16 v[10:13], v[174:177], v[222:225], v[10:13]
	s_waitcnt lgkmcnt(6)
	v_mfma_f32_16x16x32_bf16 v[14:17], v[142:145], v[226:229], v[14:17]
	v_mfma_f32_16x16x32_bf16 v[10:13], v[178:181], v[226:229], v[10:13]
	s_waitcnt lgkmcnt(3)
	v_mfma_f32_16x16x32_bf16 v[14:17], v[146:149], v[230:233], v[14:17]
	v_mfma_f32_16x16x32_bf16 v[10:13], v[182:185], v[230:233], v[10:13]
	s_waitcnt lgkmcnt(0)
	v_mfma_f32_16x16x32_bf16 v[14:17], v[170:173], v[234:237], v[14:17]
	v_mfma_f32_16x16x32_bf16 v[10:13], v[18:21], v[234:237], v[10:13]
	s_waitcnt vmcnt(28)
	ds_write_b128 v41, v[78:81]
	ds_write_b128 v41, v[82:85] offset:128
	ds_write_b128 v41, v[86:89] offset:34816
	ds_write_b128 v41, v[90:93] offset:34944
	s_waitcnt lgkmcnt(0)
	global_load_dwordx4 v[78:81], v[34:35], off offset:2560
	global_load_dwordx4 v[82:85], v[34:35], off offset:2688
	global_load_dwordx4 v[86:89], v[32:33], off offset:2560
	global_load_dwordx4 v[90:93], v[32:33], off offset:2688
	s_barrier
; #define LDSBAR() do { asm volatile("s_waitcnt lgkmcnt(0)" ::: "memory"); __builtin_amdgcn_s_barrier(); asm volatile("" ::: "memory"); } while (0)
; #define SG_LOAD(R, s_) do { if ((s_) < ns) { R.a0 = NTL((const GAS v4u*)(ap + (s_) * 128)); R.a1 = NTL((const GAS v4u*)(ap + (s_) * 128 + 64)); R.b0 = NTL((const GAS v4u*)(bp + (s_) * 128)); R.b1 = NTL((const GAS v4u*)(bp + (s_) * 128 + 64)); } } while (0)
; #define SG_STORE(R, b_) do { *(LAS v4u*)(As + (b_) * BUF + prow * LDT + pk) = R.a0; *(LAS v4u*)(As + (b_) * BUF + prow * LDT + pk + 64) = R.a1; *(LAS v4u*)(Bs + (b_) * BUF + prow * LDT + pk) = R.b0; *(LAS v4u*)(Bs + (b_) * BUF + prow * LDT + pk + 64) = R.b1; } while (0)
; template <class Epi>
; __device__ __forceinline__ void small_gemm(const Frame& F, const bf16* A, const bf16* Bt, int row_base, int K, const Epi E) {
;     ...
;         for (int s = 0; s < ns; s += 4) {
;             SG_LOAD(R3, s + 3); SG_COMP(0); if (s + 1 < ns) SG_STORE(R1, 1); LDSBAR(); if (s + 1 >= ns) break;
;             SG_LOAD(R0, s + 4); SG_COMP(1); if (s + 2 < ns) SG_STORE(R2, 0); LDSBAR(); if (s + 2 >= ns) break;
;             SG_LOAD(R1, s + 5); SG_COMP(0); if (s + 3 < ns) SG_STORE(R3, 1); LDSBAR(); if (s + 3 >= ns) break;
;             SG_LOAD(R2, s + 6); SG_COMP(1); if (s + 4 < ns) SG_STORE(R0, 0); LDSBAR();
;         }
	ds_read_b128 v[222:225], v42
	ds_read_b128 v[238:241], v43 offset:34816
	ds_read_b128 v[174:177], v43 offset:39168
	ds_read_b128 v[226:229], v42 offset:64
	ds_read_b128 v[142:145], v43 offset:34880
	ds_read_b128 v[178:181], v43 offset:39232
	ds_read_b128 v[230:233], v42 offset:128
	ds_read_b128 v[146:149], v43 offset:34944
	ds_read_b128 v[182:185], v43 offset:39296
	ds_read_b128 v[234:237], v42 offset:192
	ds_read_b128 v[170:173], v43 offset:35008
	ds_read_b128 v[18:21], v43 offset:39360
	s_waitcnt lgkmcnt(9)
	v_mfma_f32_16x16x32_bf16 v[14:17], v[238:241], v[222:225], v[14:17]
	v_mfma_f32_16x16x32_bf16 v[10:13], v[174:177], v[222:225], v[10:13]
	s_waitcnt lgkmcnt(6)
	v_mfma_f32_16x16x32_bf16 v[14:17], v[142:145], v[226:229], v[14:17]
	v_mfma_f32_16x16x32_bf16 v[10:13], v[178:181], v[226:229], v[10:13]
	s_waitcnt lgkmcnt(3)
	v_mfma_f32_16x16x32_bf16 v[14:17], v[146:149], v[230:233], v[14:17]
	v_mfma_f32_16x16x32_bf16 v[10:13], v[182:185], v[230:233], v[10:13]
	s_waitcnt lgkmcnt(0)
	v_mfma_f32_16x16x32_bf16 v[14:17], v[170:173], v[234:237], v[14:17]
	v_mfma_f32_16x16x32_bf16 v[10:13], v[18:21], v[234:237], v[10:13]
	s_waitcnt vmcnt(28)
	ds_write_b128 v41, v[94:97] offset:17408
	ds_write_b128 v41, v[98:101] offset:17536
	ds_write_b128 v41, v[102:105] offset:52224
	ds_write_b128 v41, v[106:109] offset:52352
	s_waitcnt lgkmcnt(0)
	global_load_dwordx4 v[94:97], v[34:35], off offset:2816
	global_load_dwordx4 v[98:101], v[34:35], off offset:2944
	global_load_dwordx4 v[102:105], v[32:33], off offset:2816
	global_load_dwordx4 v[106:109], v[32:33], off offset:2944
	s_barrier
	ds_read_b128 v[222:225], v42 offset:17408
	ds_read_b128 v[238:241], v43 offset:52224
	ds_read_b128 v[174:177], v43 offset:56576
	ds_read_b128 v[226:229], v42 offset:17472
	ds_read_b128 v[142:145], v43 offset:52288
	ds_read_b128 v[178:181], v43 offset:56640
	ds_read_b128 v[230:233], v42 offset:17536
	ds_read_b128 v[146:149], v43 offset:52352
	ds_read_b128 v[182:185], v43 offset:56704
	ds_read_b128 v[234:237], v42 offset:17600
	ds_read_b128 v[170:173], v43 offset:52416
	ds_read_b128 v[18:21], v43 offset:56768
	s_waitcnt lgkmcnt(9)
	v_mfma_f32_16x16x32_bf16 v[14:17], v[238:241], v[222:225], v[14:17]
	v_mfma_f32_16x16x32_bf16 v[10:13], v[174:177], v[222:225], v[10:13]
	s_waitcnt lgkmcnt(6)
	v_mfma_f32_16x16x32_bf16 v[14:17], v[142:145], v[226:229], v[14:17]
	v_mfma_f32_16x16x32_bf16 v[10:13], v[178:181], v[226:229], v[10:13]
	s_waitcnt lgkmcnt(3)
	v_mfma_f32_16x16x32_bf16 v[14:17], v[146:149], v[230:233], v[14:17]
	v_mfma_f32_16x16x32_bf16 v[10:13], v[182:185], v[230:233], v[10:13]
	s_waitcnt lgkmcnt(0)
	v_mfma_f32_16x16x32_bf16 v[14:17], v[170:173], v[234:237], v[14:17]
	v_mfma_f32_16x16x32_bf16 v[10:13], v[18:21], v[234:237], v[10:13]
	s_waitcnt vmcnt(28)
	ds_write_b128 v41, v[110:113]
	ds_write_b128 v41, v[114:117] offset:128
	ds_write_b128 v41, v[118:121] offset:34816
	ds_write_b128 v41, v[122:125] offset:34944
	s_waitcnt lgkmcnt(0)
	global_load_dwordx4 v[110:113], v[34:35], off offset:3072
	global_load_dwordx4 v[114:117], v[34:35], off offset:3200
	global_load_dwordx4 v[118:121], v[32:33], off offset:3072
	global_load_dwordx4 v[122:125], v[32:33], off offset:3200
	s_barrier
	ds_read_b128 v[222:225], v42
	ds_read_b128 v[238:241], v43 offset:34816
	ds_read_b128 v[174:177], v43 offset:39168
	ds_read_b128 v[226:229], v42 offset:64
	ds_read_b128 v[142:145], v43 offset:34880
	ds_read_b128 v[178:181], v43 offset:39232
	ds_read_b128 v[230:233], v42 offset:128
	ds_read_b128 v[146:149], v43 offset:34944
	ds_read_b128 v[182:185], v43 offset:39296
	ds_read_b128 v[234:237], v42 offset:192
	ds_read_b128 v[170:173], v43 offset:35008
	ds_read_b128 v[18:21], v43 offset:39360
	s_waitcnt lgkmcnt(9)
	v_mfma_f32_16x16x32_bf16 v[14:17], v[238:241], v[222:225], v[14:17]
	v_mfma_f32_16x16x32_bf16 v[10:13], v[174:177], v[222:225], v[10:13]
	s_waitcnt lgkmcnt(6)
	v_mfma_f32_16x16x32_bf16 v[14:17], v[142:145], v[226:229], v[14:17]
	v_mfma_f32_16x16x32_bf16 v[10:13], v[178:181], v[226:229], v[10:13]
	s_waitcnt lgkmcnt(3)
	v_mfma_f32_16x16x32_bf16 v[14:17], v[146:149], v[230:233], v[14:17]
	v_mfma_f32_16x16x32_bf16 v[10:13], v[182:185], v[230:233], v[10:13]
	s_waitcnt lgkmcnt(0)
	v_mfma_f32_16x16x32_bf16 v[14:17], v[170:173], v[234:237], v[14:17]
	v_mfma_f32_16x16x32_bf16 v[10:13], v[18:21], v[234:237], v[10:13]
	s_waitcnt vmcnt(28)
	ds_write_b128 v41, v[126:129] offset:17408
	ds_write_b128 v41, v[130:133] offset:17536
	ds_write_b128 v41, v[134:137] offset:52224
	ds_write_b128 v41, v[138:141] offset:52352
	s_waitcnt lgkmcnt(0)
	global_load_dwordx4 v[126:129], v[34:35], off offset:3328
	global_load_dwordx4 v[130:133], v[34:35], off offset:3456
	global_load_dwordx4 v[134:137], v[32:33], off offset:3328
	global_load_dwordx4 v[138:141], v[32:33], off offset:3456
	s_barrier
	ds_read_b128 v[222:225], v42 offset:17408
	ds_read_b128 v[238:241], v43 offset:52224
	ds_read_b128 v[174:177], v43 offset:56576
	ds_read_b128 v[226:229], v42 offset:17472
	ds_read_b128 v[142:145], v43 offset:52288
	ds_read_b128 v[178:181], v43 offset:56640
	ds_read_b128 v[230:233], v42 offset:17536
	ds_read_b128 v[146:149], v43 offset:52352
	ds_read_b128 v[182:185], v43 offset:56704
	ds_read_b128 v[234:237], v42 offset:17600
	ds_read_b128 v[170:173], v43 offset:52416
	ds_read_b128 v[18:21], v43 offset:56768
	s_waitcnt lgkmcnt(9)
	v_mfma_f32_16x16x32_bf16 v[14:17], v[238:241], v[222:225], v[14:17]
	v_mfma_f32_16x16x32_bf16 v[10:13], v[174:177], v[222:225], v[10:13]
	s_waitcnt lgkmcnt(6)
	v_mfma_f32_16x16x32_bf16 v[14:17], v[142:145], v[226:229], v[14:17]
	v_mfma_f32_16x16x32_bf16 v[10:13], v[178:181], v[226:229], v[10:13]
	s_waitcnt lgkmcnt(3)
	v_mfma_f32_16x16x32_bf16 v[14:17], v[146:149], v[230:233], v[14:17]
	v_mfma_f32_16x16x32_bf16 v[10:13], v[182:185], v[230:233], v[10:13]
	s_waitcnt lgkmcnt(0)
	v_mfma_f32_16x16x32_bf16 v[14:17], v[170:173], v[234:237], v[14:17]
	v_mfma_f32_16x16x32_bf16 v[10:13], v[18:21], v[234:237], v[10:13]
	s_waitcnt vmcnt(28)
	ds_write_b128 v41, v[190:193]
	ds_write_b128 v41, v[194:197] offset:128
	ds_write_b128 v41, v[198:201] offset:34816
	ds_write_b128 v41, v[202:205] offset:34944
	s_waitcnt lgkmcnt(0)
	global_load_dwordx4 v[190:193], v[34:35], off offset:3584
	global_load_dwordx4 v[194:197], v[34:35], off offset:3712
	global_load_dwordx4 v[198:201], v[32:33], off offset:3584
	global_load_dwordx4 v[202:205], v[32:33], off offset:3712
	s_barrier
; #define LDSBAR() do { asm volatile("s_waitcnt lgkmcnt(0)" ::: "memory"); __builtin_amdgcn_s_barrier(); asm volatile("" ::: "memory"); } while (0)
; #define SG_LOAD(R, s_) do { if ((s_) < ns) { R.a0 = NTL((const GAS v4u*)(ap + (s_) * 128)); R.a1 = NTL((const GAS v4u*)(ap + (s_) * 128 + 64)); R.b0 = NTL((const GAS v4u*)(bp + (s_) * 128)); R.b1 = NTL((const GAS v4u*)(bp + (s_) * 128 + 64)); } } while (0)
; #define SG_STORE(R, b_) do { *(LAS v4u*)(As + (b_) * BUF + prow * LDT + pk) = R.a0; *(LAS v4u*)(As + (b_) * BUF + prow * LDT + pk + 64) = R.a1; *(LAS v4u*)(Bs + (b_) * BUF + prow * LDT + pk) = R.b0; *(LAS v4u*)(Bs + (b_) * BUF + prow * LDT + pk + 64) = R.b1; } while (0)
; template <class Epi>
; __device__ __forceinline__ void small_gemm(const Frame& F, const bf16* A, const bf16* Bt, int row_base, int K, const Epi E) {
;     ...
;         for (int s = 0; s < ns; s += 4) {
;             SG_LOAD(R3, s + 3); SG_COMP(0); if (s + 1 < ns) SG_STORE(R1, 1); LDSBAR(); if (s + 1 >= ns) break;
;             SG_LOAD(R0, s + 4); SG_COMP(1); if (s + 2 < ns) SG_STORE(R2, 0); LDSBAR(); if (s + 2 >= ns) break;
;             SG_LOAD(R1, s + 5); SG_COMP(0); if (s + 3 < ns) SG_STORE(R3, 1); LDSBAR(); if (s + 3 >= ns) break;
;             SG_LOAD(R2, s + 6); SG_COMP(1); if (s + 4 < ns) SG_STORE(R0, 0); LDSBAR();
;         }
	ds_read_b128 v[222:225], v42
	ds_read_b128 v[238:241], v43 offset:34816
	ds_read_b128 v[174:177], v43 offset:39168
	ds_read_b128 v[226:229], v42 offset:64
	ds_read_b128 v[142:145], v43 offset:34880
	ds_read_b128 v[178:181], v43 offset:39232
	ds_read_b128 v[230:233], v42 offset:128
	ds_read_b128 v[146:149], v43 offset:34944
	ds_read_b128 v[182:185], v43 offset:39296
	ds_read_b128 v[234:237], v42 offset:192
	ds_read_b128 v[170:173], v43 offset:35008
	ds_read_b128 v[18:21], v43 offset:39360
	s_waitcnt lgkmcnt(9)
	v_mfma_f32_16x16x32_bf16 v[14:17], v[238:241], v[222:225], v[14:17]
	v_mfma_f32_16x16x32_bf16 v[10:13], v[174:177], v[222:225], v[10:13]
	s_waitcnt lgkmcnt(6)
	v_mfma_f32_16x16x32_bf16 v[14:17], v[142:145], v[226:229], v[14:17]
	v_mfma_f32_16x16x32_bf16 v[10:13], v[178:181], v[226:229], v[10:13]
	s_waitcnt lgkmcnt(3)
	v_mfma_f32_16x16x32_bf16 v[14:17], v[146:149], v[230:233], v[14:17]
	v_mfma_f32_16x16x32_bf16 v[10:13], v[182:185], v[230:233], v[10:13]
	s_waitcnt lgkmcnt(0)
	v_mfma_f32_16x16x32_bf16 v[14:17], v[170:173], v[234:237], v[14:17]
	v_mfma_f32_16x16x32_bf16 v[10:13], v[18:21], v[234:237], v[10:13]
	s_waitcnt vmcnt(28)
	ds_write_b128 v41, v[206:209] offset:17408
	ds_write_b128 v41, v[210:213] offset:17536
	ds_write_b128 v41, v[214:217] offset:52224
	ds_write_b128 v41, v[218:221] offset:52352
	s_waitcnt lgkmcnt(0)
	global_load_dwordx4 v[206:209], v[34:35], off offset:3840
	global_load_dwordx4 v[210:213], v[34:35], off offset:3968
	global_load_dwordx4 v[214:217], v[32:33], off offset:3840
	global_load_dwordx4 v[218:221], v[32:33], off offset:3968
	s_barrier
	ds_read_b128 v[222:225], v42 offset:17408
	ds_read_b128 v[238:241], v43 offset:52224
	ds_read_b128 v[174:177], v43 offset:56576
	ds_read_b128 v[226:229], v42 offset:17472
	ds_read_b128 v[142:145], v43 offset:52288
	ds_read_b128 v[178:181], v43 offset:56640
	ds_read_b128 v[230:233], v42 offset:17536
	ds_read_b128 v[146:149], v43 offset:52352
	ds_read_b128 v[182:185], v43 offset:56704
	ds_read_b128 v[234:237], v42 offset:17600
	ds_read_b128 v[170:173], v43 offset:52416
	ds_read_b128 v[18:21], v43 offset:56768
	s_waitcnt lgkmcnt(9)
	v_mfma_f32_16x16x32_bf16 v[14:17], v[238:241], v[222:225], v[14:17]
	v_mfma_f32_16x16x32_bf16 v[10:13], v[174:177], v[222:225], v[10:13]
	s_waitcnt lgkmcnt(6)
	v_mfma_f32_16x16x32_bf16 v[14:17], v[142:145], v[226:229], v[14:17]
	v_mfma_f32_16x16x32_bf16 v[10:13], v[178:181], v[226:229], v[10:13]
	s_waitcnt lgkmcnt(3)
	v_mfma_f32_16x16x32_bf16 v[14:17], v[146:149], v[230:233], v[14:17]
	v_mfma_f32_16x16x32_bf16 v[10:13], v[182:185], v[230:233], v[10:13]
	s_waitcnt lgkmcnt(0)
	v_mfma_f32_16x16x32_bf16 v[14:17], v[170:173], v[234:237], v[14:17]
	v_mfma_f32_16x16x32_bf16 v[10:13], v[18:21], v[234:237], v[10:13]
	s_waitcnt vmcnt(28)
	ds_write_b128 v41, v[46:49]
	ds_write_b128 v41, v[50:53] offset:128
	ds_write_b128 v41, v[54:57] offset:34816
	ds_write_b128 v41, v[58:61] offset:34944
	s_waitcnt lgkmcnt(0)
	global_load_dwordx4 v[46:49], v[22:23], off
	global_load_dwordx4 v[50:53], v[22:23], off offset:128
	global_load_dwordx4 v[54:57], v[24:25], off
	global_load_dwordx4 v[58:61], v[24:25], off offset:128
	s_barrier
	ds_read_b128 v[222:225], v42
	ds_read_b128 v[238:241], v43 offset:34816
	ds_read_b128 v[174:177], v43 offset:39168
	ds_read_b128 v[226:229], v42 offset:64
	ds_read_b128 v[142:145], v43 offset:34880
	ds_read_b128 v[178:181], v43 offset:39232
	ds_read_b128 v[230:233], v42 offset:128
	ds_read_b128 v[146:149], v43 offset:34944
	ds_read_b128 v[182:185], v43 offset:39296
	ds_read_b128 v[234:237], v42 offset:192
	ds_read_b128 v[170:173], v43 offset:35008
	ds_read_b128 v[18:21], v43 offset:39360
	s_waitcnt lgkmcnt(9)
	v_mfma_f32_16x16x32_bf16 v[14:17], v[238:241], v[222:225], v[14:17]
	v_mfma_f32_16x16x32_bf16 v[10:13], v[174:177], v[222:225], v[10:13]
	s_waitcnt lgkmcnt(6)
	v_mfma_f32_16x16x32_bf16 v[14:17], v[142:145], v[226:229], v[14:17]
	v_mfma_f32_16x16x32_bf16 v[10:13], v[178:181], v[226:229], v[10:13]
	s_waitcnt lgkmcnt(3)
	v_mfma_f32_16x16x32_bf16 v[14:17], v[146:149], v[230:233], v[14:17]
	v_mfma_f32_16x16x32_bf16 v[10:13], v[182:185], v[230:233], v[10:13]
	s_waitcnt lgkmcnt(0)
	v_mfma_f32_16x16x32_bf16 v[14:17], v[170:173], v[234:237], v[14:17]
	v_mfma_f32_16x16x32_bf16 v[10:13], v[18:21], v[234:237], v[10:13]
	s_waitcnt vmcnt(28)
	ds_write_b128 v41, v[62:65] offset:17408
	ds_write_b128 v41, v[66:69] offset:17536
	ds_write_b128 v41, v[70:73] offset:52224
	ds_write_b128 v41, v[74:77] offset:52352
	s_waitcnt lgkmcnt(0)
	global_load_dwordx4 v[62:65], v[22:23], off offset:256
	global_load_dwordx4 v[66:69], v[22:23], off offset:384
	global_load_dwordx4 v[70:73], v[24:25], off offset:256
	global_load_dwordx4 v[74:77], v[24:25], off offset:384
	s_barrier
	ds_read_b128 v[222:225], v42 offset:17408
	ds_read_b128 v[238:241], v43 offset:52224
	ds_read_b128 v[174:177], v43 offset:56576
	ds_read_b128 v[226:229], v42 offset:17472
	ds_read_b128 v[142:145], v43 offset:52288
	ds_read_b128 v[178:181], v43 offset:56640
	ds_read_b128 v[230:233], v42 offset:17536
	ds_read_b128 v[146:149], v43 offset:52352
	ds_read_b128 v[182:185], v43 offset:56704
	ds_read_b128 v[234:237], v42 offset:17600
	ds_read_b128 v[170:173], v43 offset:52416
	ds_read_b128 v[18:21], v43 offset:56768
	s_waitcnt lgkmcnt(9)
	v_mfma_f32_16x16x32_bf16 v[14:17], v[238:241], v[222:225], v[14:17]
	v_mfma_f32_16x16x32_bf16 v[10:13], v[174:177], v[222:225], v[10:13]
	s_waitcnt lgkmcnt(6)
	v_mfma_f32_16x16x32_bf16 v[14:17], v[142:145], v[226:229], v[14:17]
	v_mfma_f32_16x16x32_bf16 v[10:13], v[178:181], v[226:229], v[10:13]
	s_waitcnt lgkmcnt(3)
	v_mfma_f32_16x16x32_bf16 v[14:17], v[146:149], v[230:233], v[14:17]
	v_mfma_f32_16x16x32_bf16 v[10:13], v[182:185], v[230:233], v[10:13]
	s_waitcnt lgkmcnt(0)
	v_mfma_f32_16x16x32_bf16 v[14:17], v[170:173], v[234:237], v[14:17]
	v_mfma_f32_16x16x32_bf16 v[10:13], v[18:21], v[234:237], v[10:13]
	s_waitcnt vmcnt(28)
	ds_write_b128 v41, v[78:81]
	ds_write_b128 v41, v[82:85] offset:128
	ds_write_b128 v41, v[86:89] offset:34816
	ds_write_b128 v41, v[90:93] offset:34944
	s_waitcnt lgkmcnt(0)
	global_load_dwordx4 v[78:81], v[22:23], off offset:512
	global_load_dwordx4 v[82:85], v[22:23], off offset:640
	global_load_dwordx4 v[86:89], v[24:25], off offset:512
	global_load_dwordx4 v[90:93], v[24:25], off offset:640
	s_barrier
; #define LDSBAR() do { asm volatile("s_waitcnt lgkmcnt(0)" ::: "memory"); __builtin_amdgcn_s_barrier(); asm volatile("" ::: "memory"); } while (0)
; #define SG_LOAD(R, s_) do { if ((s_) < ns) { R.a0 = NTL((const GAS v4u*)(ap + (s_) * 128)); R.a1 = NTL((const GAS v4u*)(ap + (s_) * 128 + 64)); R.b0 = NTL((const GAS v4u*)(bp + (s_) * 128)); R.b1 = NTL((const GAS v4u*)(bp + (s_) * 128 + 64)); } } while (0)
; #define SG_STORE(R, b_) do { *(LAS v4u*)(As + (b_) * BUF + prow * LDT + pk) = R.a0; *(LAS v4u*)(As + (b_) * BUF + prow * LDT + pk + 64) = R.a1; *(LAS v4u*)(Bs + (b_) * BUF + prow * LDT + pk) = R.b0; *(LAS v4u*)(Bs + (b_) * BUF + prow * LDT + pk + 64) = R.b1; } while (0)
; template <class Epi>
; __device__ __forceinline__ void small_gemm(const Frame& F, const bf16* A, const bf16* Bt, int row_base, int K, const Epi E) {
;     ...
;         for (int s = 0; s < ns; s += 4) {
;             SG_LOAD(R3, s + 3); SG_COMP(0); if (s + 1 < ns) SG_STORE(R1, 1); LDSBAR(); if (s + 1 >= ns) break;
;             SG_LOAD(R0, s + 4); SG_COMP(1); if (s + 2 < ns) SG_STORE(R2, 0); LDSBAR(); if (s + 2 >= ns) break;
;             SG_LOAD(R1, s + 5); SG_COMP(0); if (s + 3 < ns) SG_STORE(R3, 1); LDSBAR(); if (s + 3 >= ns) break;
;             SG_LOAD(R2, s + 6); SG_COMP(1); if (s + 4 < ns) SG_STORE(R0, 0); LDSBAR();
;         }
	ds_read_b128 v[222:225], v42
	ds_read_b128 v[238:241], v43 offset:34816
	ds_read_b128 v[174:177], v43 offset:39168
	ds_read_b128 v[226:229], v42 offset:64
	ds_read_b128 v[142:145], v43 offset:34880
	ds_read_b128 v[178:181], v43 offset:39232
	ds_read_b128 v[230:233], v42 offset:128
	ds_read_b128 v[146:149], v43 offset:34944
	ds_read_b128 v[182:185], v43 offset:39296
	ds_read_b128 v[234:237], v42 offset:192
	ds_read_b128 v[170:173], v43 offset:35008
	ds_read_b128 v[18:21], v43 offset:39360
	s_waitcnt lgkmcnt(9)
	v_mfma_f32_16x16x32_bf16 v[14:17], v[238:241], v[222:225], v[14:17]
	v_mfma_f32_16x16x32_bf16 v[10:13], v[174:177], v[222:225], v[10:13]
	s_waitcnt lgkmcnt(6)
	v_mfma_f32_16x16x32_bf16 v[14:17], v[142:145], v[226:229], v[14:17]
	v_mfma_f32_16x16x32_bf16 v[10:13], v[178:181], v[226:229], v[10:13]
	s_waitcnt lgkmcnt(3)
	v_mfma_f32_16x16x32_bf16 v[14:17], v[146:149], v[230:233], v[14:17]
	v_mfma_f32_16x16x32_bf16 v[10:13], v[182:185], v[230:233], v[10:13]
	s_waitcnt lgkmcnt(0)
	v_mfma_f32_16x16x32_bf16 v[14:17], v[170:173], v[234:237], v[14:17]
	v_mfma_f32_16x16x32_bf16 v[10:13], v[18:21], v[234:237], v[10:13]
	s_waitcnt vmcnt(28)
	ds_write_b128 v41, v[94:97] offset:17408
	ds_write_b128 v41, v[98:101] offset:17536
	ds_write_b128 v41, v[102:105] offset:52224
	ds_write_b128 v41, v[106:109] offset:52352
	s_waitcnt lgkmcnt(0)
	global_load_dwordx4 v[94:97], v[22:23], off offset:768
	global_load_dwordx4 v[98:101], v[22:23], off offset:896
	global_load_dwordx4 v[102:105], v[24:25], off offset:768
	global_load_dwordx4 v[106:109], v[24:25], off offset:896
	s_barrier
	ds_read_b128 v[222:225], v42 offset:17408
	ds_read_b128 v[238:241], v43 offset:52224
	ds_read_b128 v[174:177], v43 offset:56576
	ds_read_b128 v[226:229], v42 offset:17472
	ds_read_b128 v[142:145], v43 offset:52288
	ds_read_b128 v[178:181], v43 offset:56640
	ds_read_b128 v[230:233], v42 offset:17536
	ds_read_b128 v[146:149], v43 offset:52352
	ds_read_b128 v[182:185], v43 offset:56704
	ds_read_b128 v[234:237], v42 offset:17600
	ds_read_b128 v[170:173], v43 offset:52416
	ds_read_b128 v[18:21], v43 offset:56768
	s_waitcnt lgkmcnt(9)
	v_mfma_f32_16x16x32_bf16 v[14:17], v[238:241], v[222:225], v[14:17]
	v_mfma_f32_16x16x32_bf16 v[10:13], v[174:177], v[222:225], v[10:13]
	s_waitcnt lgkmcnt(6)
	v_mfma_f32_16x16x32_bf16 v[14:17], v[142:145], v[226:229], v[14:17]
	v_mfma_f32_16x16x32_bf16 v[10:13], v[178:181], v[226:229], v[10:13]
	s_waitcnt lgkmcnt(3)
	v_mfma_f32_16x16x32_bf16 v[14:17], v[146:149], v[230:233], v[14:17]
	v_mfma_f32_16x16x32_bf16 v[10:13], v[182:185], v[230:233], v[10:13]
	s_waitcnt lgkmcnt(0)
	v_mfma_f32_16x16x32_bf16 v[14:17], v[170:173], v[234:237], v[14:17]
	v_mfma_f32_16x16x32_bf16 v[10:13], v[18:21], v[234:237], v[10:13]
	s_waitcnt vmcnt(28)
	ds_write_b128 v41, v[110:113]
	ds_write_b128 v41, v[114:117] offset:128
	ds_write_b128 v41, v[118:121] offset:34816
	ds_write_b128 v41, v[122:125] offset:34944
	s_waitcnt lgkmcnt(0)
	global_load_dwordx4 v[110:113], v[22:23], off offset:1024
	global_load_dwordx4 v[114:117], v[22:23], off offset:1152
	global_load_dwordx4 v[118:121], v[24:25], off offset:1024
	global_load_dwordx4 v[122:125], v[24:25], off offset:1152
	s_barrier
	ds_read_b128 v[222:225], v42
	ds_read_b128 v[238:241], v43 offset:34816
	ds_read_b128 v[174:177], v43 offset:39168
	ds_read_b128 v[226:229], v42 offset:64
	ds_read_b128 v[142:145], v43 offset:34880
	ds_read_b128 v[178:181], v43 offset:39232
	ds_read_b128 v[230:233], v42 offset:128
	ds_read_b128 v[146:149], v43 offset:34944
	ds_read_b128 v[182:185], v43 offset:39296
	ds_read_b128 v[234:237], v42 offset:192
	ds_read_b128 v[170:173], v43 offset:35008
	ds_read_b128 v[18:21], v43 offset:39360
	s_waitcnt lgkmcnt(9)
	v_mfma_f32_16x16x32_bf16 v[14:17], v[238:241], v[222:225], v[14:17]
	v_mfma_f32_16x16x32_bf16 v[10:13], v[174:177], v[222:225], v[10:13]
	s_waitcnt lgkmcnt(6)
	v_mfma_f32_16x16x32_bf16 v[14:17], v[142:145], v[226:229], v[14:17]
	v_mfma_f32_16x16x32_bf16 v[10:13], v[178:181], v[226:229], v[10:13]
	s_waitcnt lgkmcnt(3)
	v_mfma_f32_16x16x32_bf16 v[14:17], v[146:149], v[230:233], v[14:17]
	v_mfma_f32_16x16x32_bf16 v[10:13], v[182:185], v[230:233], v[10:13]
	s_waitcnt lgkmcnt(0)
	v_mfma_f32_16x16x32_bf16 v[14:17], v[170:173], v[234:237], v[14:17]
	v_mfma_f32_16x16x32_bf16 v[10:13], v[18:21], v[234:237], v[10:13]
	s_waitcnt vmcnt(28)
	ds_write_b128 v41, v[126:129] offset:17408
	ds_write_b128 v41, v[130:133] offset:17536
	ds_write_b128 v41, v[134:137] offset:52224
	ds_write_b128 v41, v[138:141] offset:52352
	s_waitcnt lgkmcnt(0)
	global_load_dwordx4 v[126:129], v[22:23], off offset:1280
	global_load_dwordx4 v[130:133], v[22:23], off offset:1408
	global_load_dwordx4 v[134:137], v[24:25], off offset:1280
	global_load_dwordx4 v[138:141], v[24:25], off offset:1408
	s_barrier
	ds_read_b128 v[222:225], v42 offset:17408
	ds_read_b128 v[238:241], v43 offset:52224
	ds_read_b128 v[174:177], v43 offset:56576
	ds_read_b128 v[226:229], v42 offset:17472
	ds_read_b128 v[142:145], v43 offset:52288
	ds_read_b128 v[178:181], v43 offset:56640
	ds_read_b128 v[230:233], v42 offset:17536
	ds_read_b128 v[146:149], v43 offset:52352
	ds_read_b128 v[182:185], v43 offset:56704
	ds_read_b128 v[234:237], v42 offset:17600
	ds_read_b128 v[170:173], v43 offset:52416
	ds_read_b128 v[18:21], v43 offset:56768
	s_waitcnt lgkmcnt(9)
	v_mfma_f32_16x16x32_bf16 v[14:17], v[238:241], v[222:225], v[14:17]
	v_mfma_f32_16x16x32_bf16 v[10:13], v[174:177], v[222:225], v[10:13]
	s_waitcnt lgkmcnt(6)
	v_mfma_f32_16x16x32_bf16 v[14:17], v[142:145], v[226:229], v[14:17]
	v_mfma_f32_16x16x32_bf16 v[10:13], v[178:181], v[226:229], v[10:13]
	s_waitcnt lgkmcnt(3)
	v_mfma_f32_16x16x32_bf16 v[14:17], v[146:149], v[230:233], v[14:17]
	v_mfma_f32_16x16x32_bf16 v[10:13], v[182:185], v[230:233], v[10:13]
	s_waitcnt lgkmcnt(0)
	v_mfma_f32_16x16x32_bf16 v[14:17], v[170:173], v[234:237], v[14:17]
	v_mfma_f32_16x16x32_bf16 v[10:13], v[18:21], v[234:237], v[10:13]
	s_waitcnt vmcnt(28)
	ds_write_b128 v41, v[190:193]
	ds_write_b128 v41, v[194:197] offset:128
	ds_write_b128 v41, v[198:201] offset:34816
	ds_write_b128 v41, v[202:205] offset:34944
	s_waitcnt lgkmcnt(0)
	s_barrier
; #define LDSBAR() do { asm volatile("s_waitcnt lgkmcnt(0)" ::: "memory"); __builtin_amdgcn_s_barrier(); asm volatile("" ::: "memory"); } while (0)
; #define SG_LOAD(R, s_) do { if ((s_) < ns) { R.a0 = NTL((const GAS v4u*)(ap + (s_) * 128)); R.a1 = NTL((const GAS v4u*)(ap + (s_) * 128 + 64)); R.b0 = NTL((const GAS v4u*)(bp + (s_) * 128)); R.b1 = NTL((const GAS v4u*)(bp + (s_) * 128 + 64)); } } while (0)
; #define SG_STORE(R, b_) do { *(LAS v4u*)(As + (b_) * BUF + prow * LDT + pk) = R.a0; *(LAS v4u*)(As + (b_) * BUF + prow * LDT + pk + 64) = R.a1; *(LAS v4u*)(Bs + (b_) * BUF + prow * LDT + pk) = R.b0; *(LAS v4u*)(Bs + (b_) * BUF + prow * LDT + pk + 64) = R.b1; } while (0)
; template <class Epi>
; __device__ __forceinline__ void small_gemm(const Frame& F, const bf16* A, const bf16* Bt, int row_base, int K, const Epi E) {
;     ...
;         for (int s = 0; s < ns; s += 4) {
;             SG_LOAD(R3, s + 3); SG_COMP(0); if (s + 1 < ns) SG_STORE(R1, 1); LDSBAR(); if (s + 1 >= ns) break;
;             SG_LOAD(R0, s + 4); SG_COMP(1); if (s + 2 < ns) SG_STORE(R2, 0); LDSBAR(); if (s + 2 >= ns) break;
;             SG_LOAD(R1, s + 5); SG_COMP(0); if (s + 3 < ns) SG_STORE(R3, 1); LDSBAR(); if (s + 3 >= ns) break;
;             SG_LOAD(R2, s + 6); SG_COMP(1); if (s + 4 < ns) SG_STORE(R0, 0); LDSBAR();
;         }
	ds_read_b128 v[222:225], v42
	ds_read_b128 v[238:241], v43 offset:34816
	ds_read_b128 v[174:177], v43 offset:39168
	ds_read_b128 v[226:229], v42 offset:64
	ds_read_b128 v[142:145], v43 offset:34880
	ds_read_b128 v[178:181], v43 offset:39232
	ds_read_b128 v[230:233], v42 offset:128
	ds_read_b128 v[146:149], v43 offset:34944
	ds_read_b128 v[182:185], v43 offset:39296
	ds_read_b128 v[234:237], v42 offset:192
	ds_read_b128 v[170:173], v43 offset:35008
	ds_read_b128 v[18:21], v43 offset:39360
	s_waitcnt lgkmcnt(9)
	v_mfma_f32_16x16x32_bf16 v[14:17], v[238:241], v[222:225], v[14:17]
	v_mfma_f32_16x16x32_bf16 v[10:13], v[174:177], v[222:225], v[10:13]
	s_waitcnt lgkmcnt(6)
	v_mfma_f32_16x16x32_bf16 v[14:17], v[142:145], v[226:229], v[14:17]
	v_mfma_f32_16x16x32_bf16 v[10:13], v[178:181], v[226:229], v[10:13]
	s_waitcnt lgkmcnt(3)
	v_mfma_f32_16x16x32_bf16 v[14:17], v[146:149], v[230:233], v[14:17]
	v_mfma_f32_16x16x32_bf16 v[10:13], v[182:185], v[230:233], v[10:13]
	s_waitcnt lgkmcnt(0)
	v_mfma_f32_16x16x32_bf16 v[14:17], v[170:173], v[234:237], v[14:17]
	v_mfma_f32_16x16x32_bf16 v[10:13], v[18:21], v[234:237], v[10:13]
	s_waitcnt vmcnt(24)
	ds_write_b128 v41, v[206:209] offset:17408
	ds_write_b128 v41, v[210:213] offset:17536
	ds_write_b128 v41, v[214:217] offset:52224
	ds_write_b128 v41, v[218:221] offset:52352
	s_waitcnt lgkmcnt(0)
	s_barrier
	ds_read_b128 v[222:225], v42 offset:17408
	ds_read_b128 v[238:241], v43 offset:52224
	ds_read_b128 v[174:177], v43 offset:56576
	ds_read_b128 v[226:229], v42 offset:17472
	ds_read_b128 v[142:145], v43 offset:52288
	ds_read_b128 v[178:181], v43 offset:56640
	ds_read_b128 v[230:233], v42 offset:17536
	ds_read_b128 v[146:149], v43 offset:52352
	ds_read_b128 v[182:185], v43 offset:56704
	ds_read_b128 v[234:237], v42 offset:17600
	ds_read_b128 v[170:173], v43 offset:52416
	ds_read_b128 v[18:21], v43 offset:56768
	s_waitcnt lgkmcnt(9)
	v_mfma_f32_16x16x32_bf16 v[14:17], v[238:241], v[222:225], v[14:17]
	v_mfma_f32_16x16x32_bf16 v[10:13], v[174:177], v[222:225], v[10:13]
	s_waitcnt lgkmcnt(6)
	v_mfma_f32_16x16x32_bf16 v[14:17], v[142:145], v[226:229], v[14:17]
	v_mfma_f32_16x16x32_bf16 v[10:13], v[178:181], v[226:229], v[10:13]
	s_waitcnt lgkmcnt(3)
	v_mfma_f32_16x16x32_bf16 v[14:17], v[146:149], v[230:233], v[14:17]
	v_mfma_f32_16x16x32_bf16 v[10:13], v[182:185], v[230:233], v[10:13]
	s_waitcnt lgkmcnt(0)
	v_mfma_f32_16x16x32_bf16 v[14:17], v[170:173], v[234:237], v[14:17]
	v_mfma_f32_16x16x32_bf16 v[10:13], v[18:21], v[234:237], v[10:13]
	s_waitcnt vmcnt(20)
	ds_write_b128 v41, v[46:49]
	ds_write_b128 v41, v[50:53] offset:128
	ds_write_b128 v41, v[54:57] offset:34816
	ds_write_b128 v41, v[58:61] offset:34944
	s_waitcnt lgkmcnt(0)
	s_barrier
	ds_read_b128 v[222:225], v42
	ds_read_b128 v[238:241], v43 offset:34816
	ds_read_b128 v[174:177], v43 offset:39168
	ds_read_b128 v[226:229], v42 offset:64
	ds_read_b128 v[142:145], v43 offset:34880
	ds_read_b128 v[178:181], v43 offset:39232
	ds_read_b128 v[230:233], v42 offset:128
	ds_read_b128 v[146:149], v43 offset:34944
	ds_read_b128 v[182:185], v43 offset:39296
	ds_read_b128 v[234:237], v42 offset:192
	ds_read_b128 v[170:173], v43 offset:35008
	ds_read_b128 v[18:21], v43 offset:39360
	s_waitcnt lgkmcnt(9)
	v_mfma_f32_16x16x32_bf16 v[14:17], v[238:241], v[222:225], v[14:17]
	v_mfma_f32_16x16x32_bf16 v[10:13], v[174:177], v[222:225], v[10:13]
	s_waitcnt lgkmcnt(6)
	v_mfma_f32_16x16x32_bf16 v[14:17], v[142:145], v[226:229], v[14:17]
	v_mfma_f32_16x16x32_bf16 v[10:13], v[178:181], v[226:229], v[10:13]
	s_waitcnt lgkmcnt(3)
	v_mfma_f32_16x16x32_bf16 v[14:17], v[146:149], v[230:233], v[14:17]
	v_mfma_f32_16x16x32_bf16 v[10:13], v[182:185], v[230:233], v[10:13]
	s_waitcnt lgkmcnt(0)
	v_mfma_f32_16x16x32_bf16 v[14:17], v[170:173], v[234:237], v[14:17]
	v_mfma_f32_16x16x32_bf16 v[10:13], v[18:21], v[234:237], v[10:13]
	s_waitcnt vmcnt(16)
	ds_write_b128 v41, v[62:65] offset:17408
	ds_write_b128 v41, v[66:69] offset:17536
	ds_write_b128 v41, v[70:73] offset:52224
	ds_write_b128 v41, v[74:77] offset:52352
	s_waitcnt lgkmcnt(0)
	s_barrier
	ds_read_b128 v[222:225], v42 offset:17408
	ds_read_b128 v[238:241], v43 offset:52224
	ds_read_b128 v[174:177], v43 offset:56576
	ds_read_b128 v[226:229], v42 offset:17472
	ds_read_b128 v[142:145], v43 offset:52288
	ds_read_b128 v[178:181], v43 offset:56640
	ds_read_b128 v[230:233], v42 offset:17536
	ds_read_b128 v[146:149], v43 offset:52352
	ds_read_b128 v[182:185], v43 offset:56704
	ds_read_b128 v[234:237], v42 offset:17600
	ds_read_b128 v[170:173], v43 offset:52416
	ds_read_b128 v[18:21], v43 offset:56768
	s_waitcnt lgkmcnt(9)
	v_mfma_f32_16x16x32_bf16 v[14:17], v[238:241], v[222:225], v[14:17]
	v_mfma_f32_16x16x32_bf16 v[10:13], v[174:177], v[222:225], v[10:13]
	s_waitcnt lgkmcnt(6)
	v_mfma_f32_16x16x32_bf16 v[14:17], v[142:145], v[226:229], v[14:17]
	v_mfma_f32_16x16x32_bf16 v[10:13], v[178:181], v[226:229], v[10:13]
	s_waitcnt lgkmcnt(3)
	v_mfma_f32_16x16x32_bf16 v[14:17], v[146:149], v[230:233], v[14:17]
	v_mfma_f32_16x16x32_bf16 v[10:13], v[182:185], v[230:233], v[10:13]
	s_waitcnt lgkmcnt(0)
	v_mfma_f32_16x16x32_bf16 v[14:17], v[170:173], v[234:237], v[14:17]
	v_mfma_f32_16x16x32_bf16 v[10:13], v[18:21], v[234:237], v[10:13]
	s_waitcnt vmcnt(12)
	ds_write_b128 v41, v[78:81]
	ds_write_b128 v41, v[82:85] offset:128
	ds_write_b128 v41, v[86:89] offset:34816
	ds_write_b128 v41, v[90:93] offset:34944
	s_waitcnt lgkmcnt(0)
	s_barrier
; #define LDSBAR() do { asm volatile("s_waitcnt lgkmcnt(0)" ::: "memory"); __builtin_amdgcn_s_barrier(); asm volatile("" ::: "memory"); } while (0)
; #define SG_LOAD(R, s_) do { if ((s_) < ns) { R.a0 = NTL((const GAS v4u*)(ap + (s_) * 128)); R.a1 = NTL((const GAS v4u*)(ap + (s_) * 128 + 64)); R.b0 = NTL((const GAS v4u*)(bp + (s_) * 128)); R.b1 = NTL((const GAS v4u*)(bp + (s_) * 128 + 64)); } } while (0)
; #define SG_STORE(R, b_) do { *(LAS v4u*)(As + (b_) * BUF + prow * LDT + pk) = R.a0; *(LAS v4u*)(As + (b_) * BUF + prow * LDT + pk + 64) = R.a1; *(LAS v4u*)(Bs + (b_) * BUF + prow * LDT + pk) = R.b0; *(LAS v4u*)(Bs + (b_) * BUF + prow * LDT + pk + 64) = R.b1; } while (0)
; template <class Epi>
; __device__ __forceinline__ void small_gemm(const Frame& F, const bf16* A, const bf16* Bt, int row_base, int K, const Epi E) {
;     ...
;         SgPre R0, R1, R2, R3;
;         SG_LOAD(R0, 0); SG_LOAD(R1, 1); SG_LOAD(R2, 2);
;         SG_STORE(R0, 0); LDSBAR();
;         for (int s = 0; s < ns; s += 4) {
;             SG_LOAD(R3, s + 3); SG_COMP(0); if (s + 1 < ns) SG_STORE(R1, 1); LDSBAR(); if (s + 1 >= ns) break;
;             SG_LOAD(R0, s + 4); SG_COMP(1); if (s + 2 < ns) SG_STORE(R2, 0); LDSBAR(); if (s + 2 >= ns) break;
;             SG_LOAD(R1, s + 5); SG_COMP(0); if (s + 3 < ns) SG_STORE(R3, 1); LDSBAR(); if (s + 3 >= ns) break;
;             SG_LOAD(R2, s + 6); SG_COMP(1); if (s + 4 < ns) SG_STORE(R0, 0); LDSBAR();
;         }
;     ...
;         { float ss = E.store4p(r0 + 16 * (w & 3) + r, c0 + 32 * (w >> 2) + 4 * q, acc0, ep0);
;           ss += E.store4p(r0 + 16 * (w & 3) + r, c0 + 32 * (w >> 2) + 16 + 4 * q, acc1, ep1);
	ds_read_b128 v[222:225], v42
	ds_read_b128 v[238:241], v43 offset:34816
	ds_read_b128 v[174:177], v43 offset:39168
	ds_read_b128 v[226:229], v42 offset:64
	ds_read_b128 v[142:145], v43 offset:34880
	ds_read_b128 v[178:181], v43 offset:39232
	ds_read_b128 v[230:233], v42 offset:128
	ds_read_b128 v[146:149], v43 offset:34944
	ds_read_b128 v[182:185], v43 offset:39296
	ds_read_b128 v[234:237], v42 offset:192
	ds_read_b128 v[170:173], v43 offset:35008
	ds_read_b128 v[18:21], v43 offset:39360
	s_waitcnt lgkmcnt(9)
	v_mfma_f32_16x16x32_bf16 v[14:17], v[238:241], v[222:225], v[14:17]
	v_mfma_f32_16x16x32_bf16 v[10:13], v[174:177], v[222:225], v[10:13]
	s_waitcnt lgkmcnt(6)
	v_mfma_f32_16x16x32_bf16 v[14:17], v[142:145], v[226:229], v[14:17]
	v_mfma_f32_16x16x32_bf16 v[10:13], v[178:181], v[226:229], v[10:13]
	s_waitcnt lgkmcnt(3)
	v_mfma_f32_16x16x32_bf16 v[14:17], v[146:149], v[230:233], v[14:17]
	v_mfma_f32_16x16x32_bf16 v[10:13], v[182:185], v[230:233], v[10:13]
	s_waitcnt lgkmcnt(0)
	v_mfma_f32_16x16x32_bf16 v[14:17], v[170:173], v[234:237], v[14:17]
	v_mfma_f32_16x16x32_bf16 v[10:13], v[18:21], v[234:237], v[10:13]
	s_waitcnt vmcnt(8)
	ds_write_b128 v41, v[94:97] offset:17408
	ds_write_b128 v41, v[98:101] offset:17536
	ds_write_b128 v41, v[102:105] offset:52224
	ds_write_b128 v41, v[106:109] offset:52352
	s_waitcnt lgkmcnt(0)
	s_barrier
	ds_read_b128 v[222:225], v42 offset:17408
	ds_read_b128 v[238:241], v43 offset:52224
	ds_read_b128 v[174:177], v43 offset:56576
	ds_read_b128 v[226:229], v42 offset:17472
	ds_read_b128 v[142:145], v43 offset:52288
	ds_read_b128 v[178:181], v43 offset:56640
	ds_read_b128 v[230:233], v42 offset:17536
	ds_read_b128 v[146:149], v43 offset:52352
	ds_read_b128 v[182:185], v43 offset:56704
	ds_read_b128 v[234:237], v42 offset:17600
	ds_read_b128 v[170:173], v43 offset:52416
	ds_read_b128 v[18:21], v43 offset:56768
	s_waitcnt lgkmcnt(9)
	v_mfma_f32_16x16x32_bf16 v[14:17], v[238:241], v[222:225], v[14:17]
	v_mfma_f32_16x16x32_bf16 v[10:13], v[174:177], v[222:225], v[10:13]
	s_waitcnt lgkmcnt(6)
	v_mfma_f32_16x16x32_bf16 v[14:17], v[142:145], v[226:229], v[14:17]
	v_mfma_f32_16x16x32_bf16 v[10:13], v[178:181], v[226:229], v[10:13]
	s_waitcnt lgkmcnt(3)
	v_mfma_f32_16x16x32_bf16 v[14:17], v[146:149], v[230:233], v[14:17]
	v_mfma_f32_16x16x32_bf16 v[10:13], v[182:185], v[230:233], v[10:13]
	s_waitcnt lgkmcnt(0)
	v_mfma_f32_16x16x32_bf16 v[14:17], v[170:173], v[234:237], v[14:17]
	v_mfma_f32_16x16x32_bf16 v[10:13], v[18:21], v[234:237], v[10:13]
	s_waitcnt vmcnt(4)
	ds_write_b128 v41, v[110:113]
	ds_write_b128 v41, v[114:117] offset:128
	ds_write_b128 v41, v[118:121] offset:34816
	ds_write_b128 v41, v[122:125] offset:34944
	s_waitcnt lgkmcnt(0)
	s_barrier
	ds_read_b128 v[222:225], v42
	ds_read_b128 v[238:241], v43 offset:34816
	ds_read_b128 v[174:177], v43 offset:39168
	ds_read_b128 v[226:229], v42 offset:64
	ds_read_b128 v[142:145], v43 offset:34880
	ds_read_b128 v[178:181], v43 offset:39232
	ds_read_b128 v[230:233], v42 offset:128
	ds_read_b128 v[146:149], v43 offset:34944
	ds_read_b128 v[182:185], v43 offset:39296
	ds_read_b128 v[234:237], v42 offset:192
	ds_read_b128 v[170:173], v43 offset:35008
	ds_read_b128 v[18:21], v43 offset:39360
	s_waitcnt lgkmcnt(9)
	v_mfma_f32_16x16x32_bf16 v[14:17], v[238:241], v[222:225], v[14:17]
	v_mfma_f32_16x16x32_bf16 v[10:13], v[174:177], v[222:225], v[10:13]
	s_waitcnt lgkmcnt(6)
	v_mfma_f32_16x16x32_bf16 v[14:17], v[142:145], v[226:229], v[14:17]
	v_mfma_f32_16x16x32_bf16 v[10:13], v[178:181], v[226:229], v[10:13]
	s_waitcnt lgkmcnt(3)
	v_mfma_f32_16x16x32_bf16 v[14:17], v[146:149], v[230:233], v[14:17]
	v_mfma_f32_16x16x32_bf16 v[10:13], v[182:185], v[230:233], v[10:13]
	s_waitcnt lgkmcnt(0)
	v_mfma_f32_16x16x32_bf16 v[14:17], v[170:173], v[234:237], v[14:17]
	v_mfma_f32_16x16x32_bf16 v[10:13], v[18:21], v[234:237], v[10:13]
	s_waitcnt vmcnt(0)
	ds_write_b128 v41, v[126:129] offset:17408
	ds_write_b128 v41, v[130:133] offset:17536
	ds_write_b128 v41, v[134:137] offset:52224
	ds_write_b128 v41, v[138:141] offset:52352
	s_waitcnt lgkmcnt(0)
	s_barrier
	ds_read_b128 v[222:225], v42 offset:17408
	ds_read_b128 v[238:241], v43 offset:52224
	ds_read_b128 v[174:177], v43 offset:56576
	ds_read_b128 v[226:229], v42 offset:17472
	ds_read_b128 v[142:145], v43 offset:52288
	ds_read_b128 v[178:181], v43 offset:56640
	ds_read_b128 v[230:233], v42 offset:17536
	ds_read_b128 v[146:149], v43 offset:52352
	ds_read_b128 v[182:185], v43 offset:56704
	ds_read_b128 v[234:237], v42 offset:17600
	ds_read_b128 v[170:173], v43 offset:52416
	ds_read_b128 v[18:21], v43 offset:56768
	s_waitcnt lgkmcnt(9)
	v_mfma_f32_16x16x32_bf16 v[14:17], v[238:241], v[222:225], v[14:17]
	v_mfma_f32_16x16x32_bf16 v[10:13], v[174:177], v[222:225], v[10:13]
	s_waitcnt lgkmcnt(6)
	v_mfma_f32_16x16x32_bf16 v[14:17], v[142:145], v[226:229], v[14:17]
	v_mfma_f32_16x16x32_bf16 v[10:13], v[178:181], v[226:229], v[10:13]
	s_waitcnt lgkmcnt(3)
	v_mfma_f32_16x16x32_bf16 v[14:17], v[146:149], v[230:233], v[14:17]
	v_mfma_f32_16x16x32_bf16 v[10:13], v[182:185], v[230:233], v[10:13]
	s_waitcnt lgkmcnt(0)
	v_mfma_f32_16x16x32_bf16 v[14:17], v[170:173], v[234:237], v[14:17]
	v_mfma_f32_16x16x32_bf16 v[10:13], v[18:21], v[234:237], v[10:13]
	s_barrier
	s_nop 6
	v_fma_f32 v8, v16, 0.5, v8
	v_fma_f32 v9, v17, 0.5, v9
	v_pk_fma_f32 v[6:7], v[14:15], 0.5, v[6:7] op_sel_hi:[1,0,1]
	v_pk_fma_f32 v[4:5], v[12:13], 0.5, v[4:5] op_sel_hi:[1,0,1]
	v_pk_fma_f32 v[2:3], v[10:11], 0.5, v[2:3] op_sel_hi:[1,0,1]
	global_store_dwordx4 v[30:31], v[6:9], off
	global_store_dwordx4 v[30:31], v[2:5], off offset:64
	s_cbranch_scc1 .LBB0_1876

; #define LDSBAR() do { asm volatile("s_waitcnt lgkmcnt(0)" ::: "memory"); __builtin_amdgcn_s_barrier(); asm volatile("" ::: "memory"); } while (0)
;     __device__ __forceinline__ Pre pre4(int row, int col) const { const float* sb = (row < TP) ? srcP : srcS - (size_t)TP * DM; Pre p; p.s = NTL((const f32x4*)(sb + (size_t)row * DM + col)); return p; }
;     __device__ __forceinline__ Pre pre4(int row, int col) const { const size_t o = (size_t)row * DM + col; Pre p; p.g = NTL((const v2u*)(SG + o)); p.m = (v2u){0u, 0u}; if (MODE == 1) p.m = NTL((const v2u*)(MG + o)); return p; }
; #define SG_LOAD(R, s_) do { if ((s_) < ns) { R.a0 = NTL((const GAS v4u*)(ap + (s_) * 128)); R.a1 = NTL((const GAS v4u*)(ap + (s_) * 128 + 64)); R.b0 = NTL((const GAS v4u*)(bp + (s_) * 128)); R.b1 = NTL((const GAS v4u*)(bp + (s_) * 128 + 64)); } } while (0)
; #define SG_STORE(R, b_) do { *(LAS v4u*)(As + (b_) * BUF + prow * LDT + pk) = R.a0; *(LAS v4u*)(As + (b_) * BUF + prow * LDT + pk + 64) = R.a1; *(LAS v4u*)(Bs + (b_) * BUF + prow * LDT + pk) = R.b0; *(LAS v4u*)(Bs + (b_) * BUF + prow * LDT + pk + 64) = R.b1; } while (0)
; template <class Epi>
; __device__ __forceinline__ void small_gemm(const Frame& F, const bf16* A, const bf16* Bt, int row_base, int K, const Epi E) {
;     ...
;     for (int u = F.vcu; u < 256; u += F.G) {
;         const int r0 = row_base + (u >> 4) * 64, c0 = (u & 15) * 64;
;         const bf16* ap = A + (size_t)(r0 + prow) * K + pk; const bf16* bp = Bt + (size_t)(c0 + prow) * K + pk;
;         f32x4 acc0 = {0.f, 0.f, 0.f, 0.f}, acc1 = {0.f, 0.f, 0.f, 0.f};
;         const typename Epi::Pre ep0 = E.pre4(r0 + 16 * (w & 3) + r, c0 + 32 * (w >> 2) + 4 * q), ep1 = E.pre4(r0 + 16 * (w & 3) + r, c0 + 32 * (w >> 2) + 16 + 4 * q);
;     ...
;         SgPre R0, R1, R2, R3;
;         SG_LOAD(R0, 0); SG_LOAD(R1, 1); SG_LOAD(R2, 2);
;         SG_STORE(R0, 0); LDSBAR();
;         for (int s = 0; s < ns; s += 4) {
;             SG_LOAD(R3, s + 3); SG_COMP(0); if (s + 1 < ns) SG_STORE(R1, 1); LDSBAR(); if (s + 1 >= ns) break;
;             SG_LOAD(R0, s + 4); SG_COMP(1); if (s + 2 < ns) SG_STORE(R2, 0); LDSBAR(); if (s + 2 >= ns) break;
;             SG_LOAD(R1, s + 5); SG_COMP(0); if (s + 3 < ns) SG_STORE(R3, 1); LDSBAR(); if (s + 3 >= ns) break;
;             SG_LOAD(R2, s + 6); SG_COMP(1); if (s + 4 < ns) SG_STORE(R0, 0); LDSBAR();
.LBB0_1937:
	s_and_b32 s12, s7, 0xffffffc0
	s_and_b32 s13, s3, 0x3c0
	s_add_i32 s14, s12, 0x4000
	v_add_u32_e32 v2, s13, v1
	s_add_i32 s15, s13, s2
	v_add_u32_e32 v3, s14, v1
	v_mad_i64_i32 v[32:33], s[12:13], v2, s9, v[28:29]
	v_mad_i64_i32 v[34:35], s[12:13], v3, s9, v[26:27]
	v_or_b32_e32 v2, s14, v38
	v_ashrrev_i32_e32 v3, 31, v2
	v_or_b32_e32 v4, s15, v39
	v_lshlrev_b64 v[2:3], 12, v[2:3]
	v_ashrrev_i32_e32 v5, 31, v4
	v_lshl_add_u64 v[2:3], s[20:21], 0, v[2:3]
	v_lshl_add_u64 v[30:31], v[4:5], 2, v[2:3]
	global_load_dwordx4 v[6:9], v[30:31], off
	global_load_dwordx4 v[2:5], v[30:31], off offset:64
	s_add_i32 s11, s11, s18
	s_add_i32 s3, s3, s6
	s_add_i32 s7, s7, s8
	s_cmpk_lt_i32 s11, 0x100
	v_add_co_u32_e32 v22, vcc, 0x1000, v34
	s_nop 0
	v_addc_co_u32_e32 v23, vcc, 0, v35, vcc
	v_add_co_u32_e32 v24, vcc, 0x1000, v32
	s_nop 0
	v_addc_co_u32_e32 v25, vcc, 0, v33, vcc
	global_load_dwordx4 v[46:49], v[34:35], off
	global_load_dwordx4 v[50:53], v[34:35], off offset:128
	global_load_dwordx4 v[54:57], v[32:33], off
	global_load_dwordx4 v[58:61], v[32:33], off offset:128
	global_load_dwordx4 v[62:65], v[34:35], off offset:256
	global_load_dwordx4 v[66:69], v[34:35], off offset:384
	global_load_dwordx4 v[70:73], v[32:33], off offset:256
	global_load_dwordx4 v[74:77], v[32:33], off offset:384
	global_load_dwordx4 v[78:81], v[34:35], off offset:512
	global_load_dwordx4 v[82:85], v[34:35], off offset:640
	global_load_dwordx4 v[86:89], v[32:33], off offset:512
	global_load_dwordx4 v[90:93], v[32:33], off offset:640
	global_load_dwordx4 v[94:97], v[34:35], off offset:768
	global_load_dwordx4 v[98:101], v[34:35], off offset:896
	global_load_dwordx4 v[102:105], v[32:33], off offset:768
	global_load_dwordx4 v[106:109], v[32:33], off offset:896
	global_load_dwordx4 v[110:113], v[34:35], off offset:1024
	global_load_dwordx4 v[114:117], v[34:35], off offset:1152
	global_load_dwordx4 v[118:121], v[32:33], off offset:1024
	global_load_dwordx4 v[122:125], v[32:33], off offset:1152
	global_load_dwordx4 v[126:129], v[34:35], off offset:1280
	global_load_dwordx4 v[130:133], v[34:35], off offset:1408
	global_load_dwordx4 v[134:137], v[32:33], off offset:1280
	global_load_dwordx4 v[138:141], v[32:33], off offset:1408
	global_load_dwordx4 v[190:193], v[34:35], off offset:1536
	global_load_dwordx4 v[194:197], v[34:35], off offset:1664
	global_load_dwordx4 v[198:201], v[32:33], off offset:1536
	global_load_dwordx4 v[202:205], v[32:33], off offset:1664
	global_load_dwordx4 v[206:209], v[34:35], off offset:1792
	global_load_dwordx4 v[210:213], v[34:35], off offset:1920
	global_load_dwordx4 v[214:217], v[32:33], off offset:1792
	global_load_dwordx4 v[218:221], v[32:33], off offset:1920
	s_waitcnt vmcnt(28)
	ds_write_b128 v40, v[46:49]
	ds_write_b128 v40, v[50:53] offset:128
	ds_write_b128 v40, v[54:57] offset:34816
	ds_write_b128 v40, v[58:61] offset:34944
	s_waitcnt lgkmcnt(0)
	global_load_dwordx4 v[46:49], v[34:35], off offset:2048
	global_load_dwordx4 v[50:53], v[34:35], off offset:2176
	global_load_dwordx4 v[54:57], v[32:33], off offset:2048
	global_load_dwordx4 v[58:61], v[32:33], off offset:2176
	s_barrier
	ds_read_b128 v[222:225], v41
	ds_read_b128 v[238:241], v42 offset:34816
	ds_read_b128 v[174:177], v42 offset:39168
	ds_read_b128 v[226:229], v41 offset:64
	ds_read_b128 v[142:145], v42 offset:34880
	ds_read_b128 v[178:181], v42 offset:39232
	ds_read_b128 v[230:233], v41 offset:128
	ds_read_b128 v[146:149], v42 offset:34944
	ds_read_b128 v[182:185], v42 offset:39296
	ds_read_b128 v[234:237], v41 offset:192
	ds_read_b128 v[170:173], v42 offset:35008
	ds_read_b128 v[18:21], v42 offset:39360
	s_waitcnt lgkmcnt(9)
	v_mfma_f32_16x16x32_bf16 v[14:17], v[238:241], v[222:225], 0
	v_mfma_f32_16x16x32_bf16 v[10:13], v[174:177], v[222:225], 0
	s_waitcnt lgkmcnt(6)
	v_mfma_f32_16x16x32_bf16 v[14:17], v[142:145], v[226:229], v[14:17]
	v_mfma_f32_16x16x32_bf16 v[10:13], v[178:181], v[226:229], v[10:13]
	s_waitcnt lgkmcnt(3)
	v_mfma_f32_16x16x32_bf16 v[14:17], v[146:149], v[230:233], v[14:17]
	v_mfma_f32_16x16x32_bf16 v[10:13], v[182:185], v[230:233], v[10:13]
	s_waitcnt lgkmcnt(0)
	v_mfma_f32_16x16x32_bf16 v[14:17], v[170:173], v[234:237], v[14:17]
	v_mfma_f32_16x16x32_bf16 v[10:13], v[18:21], v[234:237], v[10:13]
	s_waitcnt vmcnt(28)
	ds_write_b128 v40, v[62:65] offset:17408
	ds_write_b128 v40, v[66:69] offset:17536
	ds_write_b128 v40, v[70:73] offset:52224
	ds_write_b128 v40, v[74:77] offset:52352
	s_waitcnt lgkmcnt(0)
	global_load_dwordx4 v[62:65], v[34:35], off offset:2304
	global_load_dwordx4 v[66:69], v[34:35], off offset:2432
	global_load_dwordx4 v[70:73], v[32:33], off offset:2304
	global_load_dwordx4 v[74:77], v[32:33], off offset:2432
	s_barrier
	ds_read_b128 v[222:225], v41 offset:17408
	ds_read_b128 v[238:241], v42 offset:52224
	ds_read_b128 v[174:177], v42 offset:56576
	ds_read_b128 v[226:229], v41 offset:17472
	ds_read_b128 v[142:145], v42 offset:52288
	ds_read_b128 v[178:181], v42 offset:56640
	ds_read_b128 v[230:233], v41 offset:17536
	ds_read_b128 v[146:149], v42 offset:52352
	ds_read_b128 v[182:185], v42 offset:56704
	ds_read_b128 v[234:237], v41 offset:17600
	ds_read_b128 v[170:173], v42 offset:52416
	ds_read_b128 v[18:21], v42 offset:56768
	s_waitcnt lgkmcnt(9)
	v_mfma_f32_16x16x32_bf16 v[14:17], v[238:241], v[222:225], v[14:17]
	v_mfma_f32_16x16x32_bf16 v[10:13], v[174:177], v[222:225], v[10:13]
	s_waitcnt lgkmcnt(6)
	v_mfma_f32_16x16x32_bf16 v[14:17], v[142:145], v[226:229], v[14:17]
	v_mfma_f32_16x16x32_bf16 v[10:13], v[178:181], v[226:229], v[10:13]
	s_waitcnt lgkmcnt(3)
	v_mfma_f32_16x16x32_bf16 v[14:17], v[146:149], v[230:233], v[14:17]
	v_mfma_f32_16x16x32_bf16 v[10:13], v[182:185], v[230:233], v[10:13]
	s_waitcnt lgkmcnt(0)
	v_mfma_f32_16x16x32_bf16 v[14:17], v[170:173], v[234:237], v[14:17]
	v_mfma_f32_16x16x32_bf16 v[10:13], v[18:21], v[234:237], v[10:13]
	s_waitcnt vmcnt(28)
	ds_write_b128 v40, v[78:81]
	ds_write_b128 v40, v[82:85] offset:128
	ds_write_b128 v40, v[86:89] offset:34816
	ds_write_b128 v40, v[90:93] offset:34944
	s_waitcnt lgkmcnt(0)
	global_load_dwordx4 v[78:81], v[34:35], off offset:2560
	global_load_dwordx4 v[82:85], v[34:35], off offset:2688
	global_load_dwordx4 v[86:89], v[32:33], off offset:2560
	global_load_dwordx4 v[90:93], v[32:33], off offset:2688
	s_barrier
; #define LDSBAR() do { asm volatile("s_waitcnt lgkmcnt(0)" ::: "memory"); __builtin_amdgcn_s_barrier(); asm volatile("" ::: "memory"); } while (0)
; #define SG_LOAD(R, s_) do { if ((s_) < ns) { R.a0 = NTL((const GAS v4u*)(ap + (s_) * 128)); R.a1 = NTL((const GAS v4u*)(ap + (s_) * 128 + 64)); R.b0 = NTL((const GAS v4u*)(bp + (s_) * 128)); R.b1 = NTL((const GAS v4u*)(bp + (s_) * 128 + 64)); } } while (0)
; #define SG_STORE(R, b_) do { *(LAS v4u*)(As + (b_) * BUF + prow * LDT + pk) = R.a0; *(LAS v4u*)(As + (b_) * BUF + prow * LDT + pk + 64) = R.a1; *(LAS v4u*)(Bs + (b_) * BUF + prow * LDT + pk) = R.b0; *(LAS v4u*)(Bs + (b_) * BUF + prow * LDT + pk + 64) = R.b1; } while (0)
; template <class Epi>
; __device__ __forceinline__ void small_gemm(const Frame& F, const bf16* A, const bf16* Bt, int row_base, int K, const Epi E) {
;     ...
;         SgPre R0, R1, R2, R3;
;         SG_LOAD(R0, 0); SG_LOAD(R1, 1); SG_LOAD(R2, 2);
;         SG_STORE(R0, 0); LDSBAR();
;         for (int s = 0; s < ns; s += 4) {
;             SG_LOAD(R3, s + 3); SG_COMP(0); if (s + 1 < ns) SG_STORE(R1, 1); LDSBAR(); if (s + 1 >= ns) break;
;             SG_LOAD(R0, s + 4); SG_COMP(1); if (s + 2 < ns) SG_STORE(R2, 0); LDSBAR(); if (s + 2 >= ns) break;
;             SG_LOAD(R1, s + 5); SG_COMP(0); if (s + 3 < ns) SG_STORE(R3, 1); LDSBAR(); if (s + 3 >= ns) break;
;             SG_LOAD(R2, s + 6); SG_COMP(1); if (s + 4 < ns) SG_STORE(R0, 0); LDSBAR();
	ds_read_b128 v[222:225], v41
	ds_read_b128 v[238:241], v42 offset:34816
	ds_read_b128 v[174:177], v42 offset:39168
	ds_read_b128 v[226:229], v41 offset:64
	ds_read_b128 v[142:145], v42 offset:34880
	ds_read_b128 v[178:181], v42 offset:39232
	ds_read_b128 v[230:233], v41 offset:128
	ds_read_b128 v[146:149], v42 offset:34944
	ds_read_b128 v[182:185], v42 offset:39296
	ds_read_b128 v[234:237], v41 offset:192
	ds_read_b128 v[170:173], v42 offset:35008
	ds_read_b128 v[18:21], v42 offset:39360
	s_waitcnt lgkmcnt(9)
	v_mfma_f32_16x16x32_bf16 v[14:17], v[238:241], v[222:225], v[14:17]
	v_mfma_f32_16x16x32_bf16 v[10:13], v[174:177], v[222:225], v[10:13]
	s_waitcnt lgkmcnt(6)
	v_mfma_f32_16x16x32_bf16 v[14:17], v[142:145], v[226:229], v[14:17]
	v_mfma_f32_16x16x32_bf16 v[10:13], v[178:181], v[226:229], v[10:13]
	s_waitcnt lgkmcnt(3)
	v_mfma_f32_16x16x32_bf16 v[14:17], v[146:149], v[230:233], v[14:17]
	v_mfma_f32_16x16x32_bf16 v[10:13], v[182:185], v[230:233], v[10:13]
	s_waitcnt lgkmcnt(0)
	v_mfma_f32_16x16x32_bf16 v[14:17], v[170:173], v[234:237], v[14:17]
	v_mfma_f32_16x16x32_bf16 v[10:13], v[18:21], v[234:237], v[10:13]
	s_waitcnt vmcnt(28)
	ds_write_b128 v40, v[94:97] offset:17408
	ds_write_b128 v40, v[98:101] offset:17536
	ds_write_b128 v40, v[102:105] offset:52224
	ds_write_b128 v40, v[106:109] offset:52352
	s_waitcnt lgkmcnt(0)
	global_load_dwordx4 v[94:97], v[34:35], off offset:2816
	global_load_dwordx4 v[98:101], v[34:35], off offset:2944
	global_load_dwordx4 v[102:105], v[32:33], off offset:2816
	global_load_dwordx4 v[106:109], v[32:33], off offset:2944
	s_barrier
	ds_read_b128 v[222:225], v41 offset:17408
	ds_read_b128 v[238:241], v42 offset:52224
	ds_read_b128 v[174:177], v42 offset:56576
	ds_read_b128 v[226:229], v41 offset:17472
	ds_read_b128 v[142:145], v42 offset:52288
	ds_read_b128 v[178:181], v42 offset:56640
	ds_read_b128 v[230:233], v41 offset:17536
	ds_read_b128 v[146:149], v42 offset:52352
	ds_read_b128 v[182:185], v42 offset:56704
	ds_read_b128 v[234:237], v41 offset:17600
	ds_read_b128 v[170:173], v42 offset:52416
	ds_read_b128 v[18:21], v42 offset:56768
	s_waitcnt lgkmcnt(9)
	v_mfma_f32_16x16x32_bf16 v[14:17], v[238:241], v[222:225], v[14:17]
	v_mfma_f32_16x16x32_bf16 v[10:13], v[174:177], v[222:225], v[10:13]
	s_waitcnt lgkmcnt(6)
	v_mfma_f32_16x16x32_bf16 v[14:17], v[142:145], v[226:229], v[14:17]
	v_mfma_f32_16x16x32_bf16 v[10:13], v[178:181], v[226:229], v[10:13]
	s_waitcnt lgkmcnt(3)
	v_mfma_f32_16x16x32_bf16 v[14:17], v[146:149], v[230:233], v[14:17]
	v_mfma_f32_16x16x32_bf16 v[10:13], v[182:185], v[230:233], v[10:13]
	s_waitcnt lgkmcnt(0)
	v_mfma_f32_16x16x32_bf16 v[14:17], v[170:173], v[234:237], v[14:17]
	v_mfma_f32_16x16x32_bf16 v[10:13], v[18:21], v[234:237], v[10:13]
	s_waitcnt vmcnt(28)
	ds_write_b128 v40, v[110:113]
	ds_write_b128 v40, v[114:117] offset:128
	ds_write_b128 v40, v[118:121] offset:34816
	ds_write_b128 v40, v[122:125] offset:34944
	s_waitcnt lgkmcnt(0)
	global_load_dwordx4 v[110:113], v[34:35], off offset:3072
	global_load_dwordx4 v[114:117], v[34:35], off offset:3200
	global_load_dwordx4 v[118:121], v[32:33], off offset:3072
	global_load_dwordx4 v[122:125], v[32:33], off offset:3200
	s_barrier
	ds_read_b128 v[222:225], v41
	ds_read_b128 v[238:241], v42 offset:34816
	ds_read_b128 v[174:177], v42 offset:39168
	ds_read_b128 v[226:229], v41 offset:64
	ds_read_b128 v[142:145], v42 offset:34880
	ds_read_b128 v[178:181], v42 offset:39232
	ds_read_b128 v[230:233], v41 offset:128
	ds_read_b128 v[146:149], v42 offset:34944
	ds_read_b128 v[182:185], v42 offset:39296
	ds_read_b128 v[234:237], v41 offset:192
	ds_read_b128 v[170:173], v42 offset:35008
	ds_read_b128 v[18:21], v42 offset:39360
	s_waitcnt lgkmcnt(9)
	v_mfma_f32_16x16x32_bf16 v[14:17], v[238:241], v[222:225], v[14:17]
	v_mfma_f32_16x16x32_bf16 v[10:13], v[174:177], v[222:225], v[10:13]
	s_waitcnt lgkmcnt(6)
	v_mfma_f32_16x16x32_bf16 v[14:17], v[142:145], v[226:229], v[14:17]
	v_mfma_f32_16x16x32_bf16 v[10:13], v[178:181], v[226:229], v[10:13]
	s_waitcnt lgkmcnt(3)
	v_mfma_f32_16x16x32_bf16 v[14:17], v[146:149], v[230:233], v[14:17]
	v_mfma_f32_16x16x32_bf16 v[10:13], v[182:185], v[230:233], v[10:13]
	s_waitcnt lgkmcnt(0)
	v_mfma_f32_16x16x32_bf16 v[14:17], v[170:173], v[234:237], v[14:17]
	v_mfma_f32_16x16x32_bf16 v[10:13], v[18:21], v[234:237], v[10:13]
	s_waitcnt vmcnt(28)
	ds_write_b128 v40, v[126:129] offset:17408
	ds_write_b128 v40, v[130:133] offset:17536
	ds_write_b128 v40, v[134:137] offset:52224
	ds_write_b128 v40, v[138:141] offset:52352
	s_waitcnt lgkmcnt(0)
	global_load_dwordx4 v[126:129], v[34:35], off offset:3328
	global_load_dwordx4 v[130:133], v[34:35], off offset:3456
	global_load_dwordx4 v[134:137], v[32:33], off offset:3328
	global_load_dwordx4 v[138:141], v[32:33], off offset:3456
	s_barrier
	ds_read_b128 v[222:225], v41 offset:17408
	ds_read_b128 v[238:241], v42 offset:52224
	ds_read_b128 v[174:177], v42 offset:56576
	ds_read_b128 v[226:229], v41 offset:17472
	ds_read_b128 v[142:145], v42 offset:52288
	ds_read_b128 v[178:181], v42 offset:56640
	ds_read_b128 v[230:233], v41 offset:17536
	ds_read_b128 v[146:149], v42 offset:52352
	ds_read_b128 v[182:185], v42 offset:56704
	ds_read_b128 v[234:237], v41 offset:17600
	ds_read_b128 v[170:173], v42 offset:52416
	ds_read_b128 v[18:21], v42 offset:56768
	s_waitcnt lgkmcnt(9)
	v_mfma_f32_16x16x32_bf16 v[14:17], v[238:241], v[222:225], v[14:17]
	v_mfma_f32_16x16x32_bf16 v[10:13], v[174:177], v[222:225], v[10:13]
	s_waitcnt lgkmcnt(6)
	v_mfma_f32_16x16x32_bf16 v[14:17], v[142:145], v[226:229], v[14:17]
	v_mfma_f32_16x16x32_bf16 v[10:13], v[178:181], v[226:229], v[10:13]
	s_waitcnt lgkmcnt(3)
	v_mfma_f32_16x16x32_bf16 v[14:17], v[146:149], v[230:233], v[14:17]
	v_mfma_f32_16x16x32_bf16 v[10:13], v[182:185], v[230:233], v[10:13]
	s_waitcnt lgkmcnt(0)
	v_mfma_f32_16x16x32_bf16 v[14:17], v[170:173], v[234:237], v[14:17]
	v_mfma_f32_16x16x32_bf16 v[10:13], v[18:21], v[234:237], v[10:13]
	s_waitcnt vmcnt(28)
	ds_write_b128 v40, v[190:193]
	ds_write_b128 v40, v[194:197] offset:128
	ds_write_b128 v40, v[198:201] offset:34816
	ds_write_b128 v40, v[202:205] offset:34944
	s_waitcnt lgkmcnt(0)
	global_load_dwordx4 v[190:193], v[34:35], off offset:3584
	global_load_dwordx4 v[194:197], v[34:35], off offset:3712
	global_load_dwordx4 v[198:201], v[32:33], off offset:3584
	global_load_dwordx4 v[202:205], v[32:33], off offset:3712
	s_barrier
; #define LDSBAR() do { asm volatile("s_waitcnt lgkmcnt(0)" ::: "memory"); __builtin_amdgcn_s_barrier(); asm volatile("" ::: "memory"); } while (0)
; #define SG_LOAD(R, s_) do { if ((s_) < ns) { R.a0 = NTL((const GAS v4u*)(ap + (s_) * 128)); R.a1 = NTL((const GAS v4u*)(ap + (s_) * 128 + 64)); R.b0 = NTL((const GAS v4u*)(bp + (s_) * 128)); R.b1 = NTL((const GAS v4u*)(bp + (s_) * 128 + 64)); } } while (0)
; #define SG_STORE(R, b_) do { *(LAS v4u*)(As + (b_) * BUF + prow * LDT + pk) = R.a0; *(LAS v4u*)(As + (b_) * BUF + prow * LDT + pk + 64) = R.a1; *(LAS v4u*)(Bs + (b_) * BUF + prow * LDT + pk) = R.b0; *(LAS v4u*)(Bs + (b_) * BUF + prow * LDT + pk + 64) = R.b1; } while (0)
; template <class Epi>
; __device__ __forceinline__ void small_gemm(const Frame& F, const bf16* A, const bf16* Bt, int row_base, int K, const Epi E) {
;     ...
;         SgPre R0, R1, R2, R3;
;         SG_LOAD(R0, 0); SG_LOAD(R1, 1); SG_LOAD(R2, 2);
;         SG_STORE(R0, 0); LDSBAR();
;         for (int s = 0; s < ns; s += 4) {
;             SG_LOAD(R3, s + 3); SG_COMP(0); if (s + 1 < ns) SG_STORE(R1, 1); LDSBAR(); if (s + 1 >= ns) break;
;             SG_LOAD(R0, s + 4); SG_COMP(1); if (s + 2 < ns) SG_STORE(R2, 0); LDSBAR(); if (s + 2 >= ns) break;
;             SG_LOAD(R1, s + 5); SG_COMP(0); if (s + 3 < ns) SG_STORE(R3, 1); LDSBAR(); if (s + 3 >= ns) break;
;             SG_LOAD(R2, s + 6); SG_COMP(1); if (s + 4 < ns) SG_STORE(R0, 0); LDSBAR();
	ds_read_b128 v[222:225], v41
	ds_read_b128 v[238:241], v42 offset:34816
	ds_read_b128 v[174:177], v42 offset:39168
	ds_read_b128 v[226:229], v41 offset:64
	ds_read_b128 v[142:145], v42 offset:34880
	ds_read_b128 v[178:181], v42 offset:39232
	ds_read_b128 v[230:233], v41 offset:128
	ds_read_b128 v[146:149], v42 offset:34944
	ds_read_b128 v[182:185], v42 offset:39296
	ds_read_b128 v[234:237], v41 offset:192
	ds_read_b128 v[170:173], v42 offset:35008
	ds_read_b128 v[18:21], v42 offset:39360
	s_waitcnt lgkmcnt(9)
	v_mfma_f32_16x16x32_bf16 v[14:17], v[238:241], v[222:225], v[14:17]
	v_mfma_f32_16x16x32_bf16 v[10:13], v[174:177], v[222:225], v[10:13]
	s_waitcnt lgkmcnt(6)
	v_mfma_f32_16x16x32_bf16 v[14:17], v[142:145], v[226:229], v[14:17]
	v_mfma_f32_16x16x32_bf16 v[10:13], v[178:181], v[226:229], v[10:13]
	s_waitcnt lgkmcnt(3)
	v_mfma_f32_16x16x32_bf16 v[14:17], v[146:149], v[230:233], v[14:17]
	v_mfma_f32_16x16x32_bf16 v[10:13], v[182:185], v[230:233], v[10:13]
	s_waitcnt lgkmcnt(0)
	v_mfma_f32_16x16x32_bf16 v[14:17], v[170:173], v[234:237], v[14:17]
	v_mfma_f32_16x16x32_bf16 v[10:13], v[18:21], v[234:237], v[10:13]
	s_waitcnt vmcnt(28)
	ds_write_b128 v40, v[206:209] offset:17408
	ds_write_b128 v40, v[210:213] offset:17536
	ds_write_b128 v40, v[214:217] offset:52224
	ds_write_b128 v40, v[218:221] offset:52352
	s_waitcnt lgkmcnt(0)
	global_load_dwordx4 v[206:209], v[34:35], off offset:3840
	global_load_dwordx4 v[210:213], v[34:35], off offset:3968
	global_load_dwordx4 v[214:217], v[32:33], off offset:3840
	global_load_dwordx4 v[218:221], v[32:33], off offset:3968
	s_barrier
	ds_read_b128 v[222:225], v41 offset:17408
	ds_read_b128 v[238:241], v42 offset:52224
	ds_read_b128 v[174:177], v42 offset:56576
	ds_read_b128 v[226:229], v41 offset:17472
	ds_read_b128 v[142:145], v42 offset:52288
	ds_read_b128 v[178:181], v42 offset:56640
	ds_read_b128 v[230:233], v41 offset:17536
	ds_read_b128 v[146:149], v42 offset:52352
	ds_read_b128 v[182:185], v42 offset:56704
	ds_read_b128 v[234:237], v41 offset:17600
	ds_read_b128 v[170:173], v42 offset:52416
	ds_read_b128 v[18:21], v42 offset:56768
	s_waitcnt lgkmcnt(9)
	v_mfma_f32_16x16x32_bf16 v[14:17], v[238:241], v[222:225], v[14:17]
	v_mfma_f32_16x16x32_bf16 v[10:13], v[174:177], v[222:225], v[10:13]
	s_waitcnt lgkmcnt(6)
	v_mfma_f32_16x16x32_bf16 v[14:17], v[142:145], v[226:229], v[14:17]
	v_mfma_f32_16x16x32_bf16 v[10:13], v[178:181], v[226:229], v[10:13]
	s_waitcnt lgkmcnt(3)
	v_mfma_f32_16x16x32_bf16 v[14:17], v[146:149], v[230:233], v[14:17]
	v_mfma_f32_16x16x32_bf16 v[10:13], v[182:185], v[230:233], v[10:13]
	s_waitcnt lgkmcnt(0)
	v_mfma_f32_16x16x32_bf16 v[14:17], v[170:173], v[234:237], v[14:17]
	v_mfma_f32_16x16x32_bf16 v[10:13], v[18:21], v[234:237], v[10:13]
	s_waitcnt vmcnt(28)
	ds_write_b128 v40, v[46:49]
	ds_write_b128 v40, v[50:53] offset:128
	ds_write_b128 v40, v[54:57] offset:34816
	ds_write_b128 v40, v[58:61] offset:34944
	s_waitcnt lgkmcnt(0)
	global_load_dwordx4 v[46:49], v[22:23], off
	global_load_dwordx4 v[50:53], v[22:23], off offset:128
	global_load_dwordx4 v[54:57], v[24:25], off
	global_load_dwordx4 v[58:61], v[24:25], off offset:128
	s_barrier
	ds_read_b128 v[222:225], v41
	ds_read_b128 v[238:241], v42 offset:34816
	ds_read_b128 v[174:177], v42 offset:39168
	ds_read_b128 v[226:229], v41 offset:64
	ds_read_b128 v[142:145], v42 offset:34880
	ds_read_b128 v[178:181], v42 offset:39232
	ds_read_b128 v[230:233], v41 offset:128
	ds_read_b128 v[146:149], v42 offset:34944
	ds_read_b128 v[182:185], v42 offset:39296
	ds_read_b128 v[234:237], v41 offset:192
	ds_read_b128 v[170:173], v42 offset:35008
	ds_read_b128 v[18:21], v42 offset:39360
	s_waitcnt lgkmcnt(9)
	v_mfma_f32_16x16x32_bf16 v[14:17], v[238:241], v[222:225], v[14:17]
	v_mfma_f32_16x16x32_bf16 v[10:13], v[174:177], v[222:225], v[10:13]
	s_waitcnt lgkmcnt(6)
	v_mfma_f32_16x16x32_bf16 v[14:17], v[142:145], v[226:229], v[14:17]
	v_mfma_f32_16x16x32_bf16 v[10:13], v[178:181], v[226:229], v[10:13]
	s_waitcnt lgkmcnt(3)
	v_mfma_f32_16x16x32_bf16 v[14:17], v[146:149], v[230:233], v[14:17]
	v_mfma_f32_16x16x32_bf16 v[10:13], v[182:185], v[230:233], v[10:13]
	s_waitcnt lgkmcnt(0)
	v_mfma_f32_16x16x32_bf16 v[14:17], v[170:173], v[234:237], v[14:17]
	v_mfma_f32_16x16x32_bf16 v[10:13], v[18:21], v[234:237], v[10:13]
	s_waitcnt vmcnt(28)
	ds_write_b128 v40, v[62:65] offset:17408
	ds_write_b128 v40, v[66:69] offset:17536
	ds_write_b128 v40, v[70:73] offset:52224
	ds_write_b128 v40, v[74:77] offset:52352
	s_waitcnt lgkmcnt(0)
	global_load_dwordx4 v[62:65], v[22:23], off offset:256
	global_load_dwordx4 v[66:69], v[22:23], off offset:384
	global_load_dwordx4 v[70:73], v[24:25], off offset:256
	global_load_dwordx4 v[74:77], v[24:25], off offset:384
	s_barrier
	ds_read_b128 v[222:225], v41 offset:17408
	ds_read_b128 v[238:241], v42 offset:52224
	ds_read_b128 v[174:177], v42 offset:56576
	ds_read_b128 v[226:229], v41 offset:17472
	ds_read_b128 v[142:145], v42 offset:52288
	ds_read_b128 v[178:181], v42 offset:56640
	ds_read_b128 v[230:233], v41 offset:17536
	ds_read_b128 v[146:149], v42 offset:52352
	ds_read_b128 v[182:185], v42 offset:56704
	ds_read_b128 v[234:237], v41 offset:17600
	ds_read_b128 v[170:173], v42 offset:52416
	ds_read_b128 v[18:21], v42 offset:56768
	s_waitcnt lgkmcnt(9)
	v_mfma_f32_16x16x32_bf16 v[14:17], v[238:241], v[222:225], v[14:17]
	v_mfma_f32_16x16x32_bf16 v[10:13], v[174:177], v[222:225], v[10:13]
	s_waitcnt lgkmcnt(6)
	v_mfma_f32_16x16x32_bf16 v[14:17], v[142:145], v[226:229], v[14:17]
	v_mfma_f32_16x16x32_bf16 v[10:13], v[178:181], v[226:229], v[10:13]
	s_waitcnt lgkmcnt(3)
	v_mfma_f32_16x16x32_bf16 v[14:17], v[146:149], v[230:233], v[14:17]
	v_mfma_f32_16x16x32_bf16 v[10:13], v[182:185], v[230:233], v[10:13]
	s_waitcnt lgkmcnt(0)
	v_mfma_f32_16x16x32_bf16 v[14:17], v[170:173], v[234:237], v[14:17]
	v_mfma_f32_16x16x32_bf16 v[10:13], v[18:21], v[234:237], v[10:13]
	s_waitcnt vmcnt(28)
	ds_write_b128 v40, v[78:81]
	ds_write_b128 v40, v[82:85] offset:128
	ds_write_b128 v40, v[86:89] offset:34816
	ds_write_b128 v40, v[90:93] offset:34944
	s_waitcnt lgkmcnt(0)
	global_load_dwordx4 v[78:81], v[22:23], off offset:512
	global_load_dwordx4 v[82:85], v[22:23], off offset:640
	global_load_dwordx4 v[86:89], v[24:25], off offset:512
	global_load_dwordx4 v[90:93], v[24:25], off offset:640
	s_barrier
; #define LDSBAR() do { asm volatile("s_waitcnt lgkmcnt(0)" ::: "memory"); __builtin_amdgcn_s_barrier(); asm volatile("" ::: "memory"); } while (0)
; #define SG_LOAD(R, s_) do { if ((s_) < ns) { R.a0 = NTL((const GAS v4u*)(ap + (s_) * 128)); R.a1 = NTL((const GAS v4u*)(ap + (s_) * 128 + 64)); R.b0 = NTL((const GAS v4u*)(bp + (s_) * 128)); R.b1 = NTL((const GAS v4u*)(bp + (s_) * 128 + 64)); } } while (0)
; #define SG_STORE(R, b_) do { *(LAS v4u*)(As + (b_) * BUF + prow * LDT + pk) = R.a0; *(LAS v4u*)(As + (b_) * BUF + prow * LDT + pk + 64) = R.a1; *(LAS v4u*)(Bs + (b_) * BUF + prow * LDT + pk) = R.b0; *(LAS v4u*)(Bs + (b_) * BUF + prow * LDT + pk + 64) = R.b1; } while (0)
; template <class Epi>
; __device__ __forceinline__ void small_gemm(const Frame& F, const bf16* A, const bf16* Bt, int row_base, int K, const Epi E) {
;     ...
;         SgPre R0, R1, R2, R3;
;         SG_LOAD(R0, 0); SG_LOAD(R1, 1); SG_LOAD(R2, 2);
;         SG_STORE(R0, 0); LDSBAR();
;         for (int s = 0; s < ns; s += 4) {
;             SG_LOAD(R3, s + 3); SG_COMP(0); if (s + 1 < ns) SG_STORE(R1, 1); LDSBAR(); if (s + 1 >= ns) break;
;             SG_LOAD(R0, s + 4); SG_COMP(1); if (s + 2 < ns) SG_STORE(R2, 0); LDSBAR(); if (s + 2 >= ns) break;
;             SG_LOAD(R1, s + 5); SG_COMP(0); if (s + 3 < ns) SG_STORE(R3, 1); LDSBAR(); if (s + 3 >= ns) break;
;             SG_LOAD(R2, s + 6); SG_COMP(1); if (s + 4 < ns) SG_STORE(R0, 0); LDSBAR();
	ds_read_b128 v[222:225], v41
	ds_read_b128 v[238:241], v42 offset:34816
	ds_read_b128 v[174:177], v42 offset:39168
	ds_read_b128 v[226:229], v41 offset:64
	ds_read_b128 v[142:145], v42 offset:34880
	ds_read_b128 v[178:181], v42 offset:39232
	ds_read_b128 v[230:233], v41 offset:128
	ds_read_b128 v[146:149], v42 offset:34944
	ds_read_b128 v[182:185], v42 offset:39296
	ds_read_b128 v[234:237], v41 offset:192
	ds_read_b128 v[170:173], v42 offset:35008
	ds_read_b128 v[18:21], v42 offset:39360
	s_waitcnt lgkmcnt(9)
	v_mfma_f32_16x16x32_bf16 v[14:17], v[238:241], v[222:225], v[14:17]
	v_mfma_f32_16x16x32_bf16 v[10:13], v[174:177], v[222:225], v[10:13]
	s_waitcnt lgkmcnt(6)
	v_mfma_f32_16x16x32_bf16 v[14:17], v[142:145], v[226:229], v[14:17]
	v_mfma_f32_16x16x32_bf16 v[10:13], v[178:181], v[226:229], v[10:13]
	s_waitcnt lgkmcnt(3)
	v_mfma_f32_16x16x32_bf16 v[14:17], v[146:149], v[230:233], v[14:17]
	v_mfma_f32_16x16x32_bf16 v[10:13], v[182:185], v[230:233], v[10:13]
	s_waitcnt lgkmcnt(0)
	v_mfma_f32_16x16x32_bf16 v[14:17], v[170:173], v[234:237], v[14:17]
	v_mfma_f32_16x16x32_bf16 v[10:13], v[18:21], v[234:237], v[10:13]
	s_waitcnt vmcnt(28)
	ds_write_b128 v40, v[94:97] offset:17408
	ds_write_b128 v40, v[98:101] offset:17536
	ds_write_b128 v40, v[102:105] offset:52224
	ds_write_b128 v40, v[106:109] offset:52352
	s_waitcnt lgkmcnt(0)
	global_load_dwordx4 v[94:97], v[22:23], off offset:768
	global_load_dwordx4 v[98:101], v[22:23], off offset:896
	global_load_dwordx4 v[102:105], v[24:25], off offset:768
	global_load_dwordx4 v[106:109], v[24:25], off offset:896
	s_barrier
	ds_read_b128 v[222:225], v41 offset:17408
	ds_read_b128 v[238:241], v42 offset:52224
	ds_read_b128 v[174:177], v42 offset:56576
	ds_read_b128 v[226:229], v41 offset:17472
	ds_read_b128 v[142:145], v42 offset:52288
	ds_read_b128 v[178:181], v42 offset:56640
	ds_read_b128 v[230:233], v41 offset:17536
	ds_read_b128 v[146:149], v42 offset:52352
	ds_read_b128 v[182:185], v42 offset:56704
	ds_read_b128 v[234:237], v41 offset:17600
	ds_read_b128 v[170:173], v42 offset:52416
	ds_read_b128 v[18:21], v42 offset:56768
	s_waitcnt lgkmcnt(9)
	v_mfma_f32_16x16x32_bf16 v[14:17], v[238:241], v[222:225], v[14:17]
	v_mfma_f32_16x16x32_bf16 v[10:13], v[174:177], v[222:225], v[10:13]
	s_waitcnt lgkmcnt(6)
	v_mfma_f32_16x16x32_bf16 v[14:17], v[142:145], v[226:229], v[14:17]
	v_mfma_f32_16x16x32_bf16 v[10:13], v[178:181], v[226:229], v[10:13]
	s_waitcnt lgkmcnt(3)
	v_mfma_f32_16x16x32_bf16 v[14:17], v[146:149], v[230:233], v[14:17]
	v_mfma_f32_16x16x32_bf16 v[10:13], v[182:185], v[230:233], v[10:13]
	s_waitcnt lgkmcnt(0)
	v_mfma_f32_16x16x32_bf16 v[14:17], v[170:173], v[234:237], v[14:17]
	v_mfma_f32_16x16x32_bf16 v[10:13], v[18:21], v[234:237], v[10:13]
	s_waitcnt vmcnt(28)
	ds_write_b128 v40, v[110:113]
	ds_write_b128 v40, v[114:117] offset:128
	ds_write_b128 v40, v[118:121] offset:34816
	ds_write_b128 v40, v[122:125] offset:34944
	s_waitcnt lgkmcnt(0)
	global_load_dwordx4 v[110:113], v[22:23], off offset:1024
	global_load_dwordx4 v[114:117], v[22:23], off offset:1152
	global_load_dwordx4 v[118:121], v[24:25], off offset:1024
	global_load_dwordx4 v[122:125], v[24:25], off offset:1152
	s_barrier
	ds_read_b128 v[222:225], v41
	ds_read_b128 v[238:241], v42 offset:34816
	ds_read_b128 v[174:177], v42 offset:39168
	ds_read_b128 v[226:229], v41 offset:64
	ds_read_b128 v[142:145], v42 offset:34880
	ds_read_b128 v[178:181], v42 offset:39232
	ds_read_b128 v[230:233], v41 offset:128
	ds_read_b128 v[146:149], v42 offset:34944
	ds_read_b128 v[182:185], v42 offset:39296
	ds_read_b128 v[234:237], v41 offset:192
	ds_read_b128 v[170:173], v42 offset:35008
	ds_read_b128 v[18:21], v42 offset:39360
	s_waitcnt lgkmcnt(9)
	v_mfma_f32_16x16x32_bf16 v[14:17], v[238:241], v[222:225], v[14:17]
	v_mfma_f32_16x16x32_bf16 v[10:13], v[174:177], v[222:225], v[10:13]
	s_waitcnt lgkmcnt(6)
	v_mfma_f32_16x16x32_bf16 v[14:17], v[142:145], v[226:229], v[14:17]
	v_mfma_f32_16x16x32_bf16 v[10:13], v[178:181], v[226:229], v[10:13]
	s_waitcnt lgkmcnt(3)
	v_mfma_f32_16x16x32_bf16 v[14:17], v[146:149], v[230:233], v[14:17]
	v_mfma_f32_16x16x32_bf16 v[10:13], v[182:185], v[230:233], v[10:13]
	s_waitcnt lgkmcnt(0)
	v_mfma_f32_16x16x32_bf16 v[14:17], v[170:173], v[234:237], v[14:17]
	v_mfma_f32_16x16x32_bf16 v[10:13], v[18:21], v[234:237], v[10:13]
	s_waitcnt vmcnt(28)
	ds_write_b128 v40, v[126:129] offset:17408
	ds_write_b128 v40, v[130:133] offset:17536
	ds_write_b128 v40, v[134:137] offset:52224
	ds_write_b128 v40, v[138:141] offset:52352
	s_waitcnt lgkmcnt(0)
	global_load_dwordx4 v[126:129], v[22:23], off offset:1280
	global_load_dwordx4 v[130:133], v[22:23], off offset:1408
	global_load_dwordx4 v[134:137], v[24:25], off offset:1280
	global_load_dwordx4 v[138:141], v[24:25], off offset:1408
	s_barrier
	ds_read_b128 v[222:225], v41 offset:17408
	ds_read_b128 v[238:241], v42 offset:52224
	ds_read_b128 v[174:177], v42 offset:56576
	ds_read_b128 v[226:229], v41 offset:17472
	ds_read_b128 v[142:145], v42 offset:52288
	ds_read_b128 v[178:181], v42 offset:56640
	ds_read_b128 v[230:233], v41 offset:17536
	ds_read_b128 v[146:149], v42 offset:52352
	ds_read_b128 v[182:185], v42 offset:56704
	ds_read_b128 v[234:237], v41 offset:17600
	ds_read_b128 v[170:173], v42 offset:52416
	ds_read_b128 v[18:21], v42 offset:56768
	s_waitcnt lgkmcnt(9)
	v_mfma_f32_16x16x32_bf16 v[14:17], v[238:241], v[222:225], v[14:17]
	v_mfma_f32_16x16x32_bf16 v[10:13], v[174:177], v[222:225], v[10:13]
	s_waitcnt lgkmcnt(6)
	v_mfma_f32_16x16x32_bf16 v[14:17], v[142:145], v[226:229], v[14:17]
	v_mfma_f32_16x16x32_bf16 v[10:13], v[178:181], v[226:229], v[10:13]
	s_waitcnt lgkmcnt(3)
	v_mfma_f32_16x16x32_bf16 v[14:17], v[146:149], v[230:233], v[14:17]
	v_mfma_f32_16x16x32_bf16 v[10:13], v[182:185], v[230:233], v[10:13]
	s_waitcnt lgkmcnt(0)
	v_mfma_f32_16x16x32_bf16 v[14:17], v[170:173], v[234:237], v[14:17]
	v_mfma_f32_16x16x32_bf16 v[10:13], v[18:21], v[234:237], v[10:13]
	s_waitcnt vmcnt(28)
	ds_write_b128 v40, v[190:193]
	ds_write_b128 v40, v[194:197] offset:128
	ds_write_b128 v40, v[198:201] offset:34816
	ds_write_b128 v40, v[202:205] offset:34944
	s_waitcnt lgkmcnt(0)
	s_barrier
; #define LDSBAR() do { asm volatile("s_waitcnt lgkmcnt(0)" ::: "memory"); __builtin_amdgcn_s_barrier(); asm volatile("" ::: "memory"); } while (0)
; #define SG_LOAD(R, s_) do { if ((s_) < ns) { R.a0 = NTL((const GAS v4u*)(ap + (s_) * 128)); R.a1 = NTL((const GAS v4u*)(ap + (s_) * 128 + 64)); R.b0 = NTL((const GAS v4u*)(bp + (s_) * 128)); R.b1 = NTL((const GAS v4u*)(bp + (s_) * 128 + 64)); } } while (0)
; #define SG_STORE(R, b_) do { *(LAS v4u*)(As + (b_) * BUF + prow * LDT + pk) = R.a0; *(LAS v4u*)(As + (b_) * BUF + prow * LDT + pk + 64) = R.a1; *(LAS v4u*)(Bs + (b_) * BUF + prow * LDT + pk) = R.b0; *(LAS v4u*)(Bs + (b_) * BUF + prow * LDT + pk + 64) = R.b1; } while (0)
; template <class Epi>
; __device__ __forceinline__ void small_gemm(const Frame& F, const bf16* A, const bf16* Bt, int row_base, int K, const Epi E) {
;     ...
;         SgPre R0, R1, R2, R3;
;         SG_LOAD(R0, 0); SG_LOAD(R1, 1); SG_LOAD(R2, 2);
;         SG_STORE(R0, 0); LDSBAR();
;         for (int s = 0; s < ns; s += 4) {
;             SG_LOAD(R3, s + 3); SG_COMP(0); if (s + 1 < ns) SG_STORE(R1, 1); LDSBAR(); if (s + 1 >= ns) break;
;             SG_LOAD(R0, s + 4); SG_COMP(1); if (s + 2 < ns) SG_STORE(R2, 0); LDSBAR(); if (s + 2 >= ns) break;
;             SG_LOAD(R1, s + 5); SG_COMP(0); if (s + 3 < ns) SG_STORE(R3, 1); LDSBAR(); if (s + 3 >= ns) break;
;             SG_LOAD(R2, s + 6); SG_COMP(1); if (s + 4 < ns) SG_STORE(R0, 0); LDSBAR();
	ds_read_b128 v[222:225], v41
	ds_read_b128 v[238:241], v42 offset:34816
	ds_read_b128 v[174:177], v42 offset:39168
	ds_read_b128 v[226:229], v41 offset:64
	ds_read_b128 v[142:145], v42 offset:34880
	ds_read_b128 v[178:181], v42 offset:39232
	ds_read_b128 v[230:233], v41 offset:128
	ds_read_b128 v[146:149], v42 offset:34944
	ds_read_b128 v[182:185], v42 offset:39296
	ds_read_b128 v[234:237], v41 offset:192
	ds_read_b128 v[170:173], v42 offset:35008
	ds_read_b128 v[18:21], v42 offset:39360
	s_waitcnt lgkmcnt(9)
	v_mfma_f32_16x16x32_bf16 v[14:17], v[238:241], v[222:225], v[14:17]
	v_mfma_f32_16x16x32_bf16 v[10:13], v[174:177], v[222:225], v[10:13]
	s_waitcnt lgkmcnt(6)
	v_mfma_f32_16x16x32_bf16 v[14:17], v[142:145], v[226:229], v[14:17]
	v_mfma_f32_16x16x32_bf16 v[10:13], v[178:181], v[226:229], v[10:13]
	s_waitcnt lgkmcnt(3)
	v_mfma_f32_16x16x32_bf16 v[14:17], v[146:149], v[230:233], v[14:17]
	v_mfma_f32_16x16x32_bf16 v[10:13], v[182:185], v[230:233], v[10:13]
	s_waitcnt lgkmcnt(0)
	v_mfma_f32_16x16x32_bf16 v[14:17], v[170:173], v[234:237], v[14:17]
	v_mfma_f32_16x16x32_bf16 v[10:13], v[18:21], v[234:237], v[10:13]
	s_waitcnt vmcnt(24)
	ds_write_b128 v40, v[206:209] offset:17408
	ds_write_b128 v40, v[210:213] offset:17536
	ds_write_b128 v40, v[214:217] offset:52224
	ds_write_b128 v40, v[218:221] offset:52352
	s_waitcnt lgkmcnt(0)
	s_barrier
	ds_read_b128 v[222:225], v41 offset:17408
	ds_read_b128 v[238:241], v42 offset:52224
	ds_read_b128 v[174:177], v42 offset:56576
	ds_read_b128 v[226:229], v41 offset:17472
	ds_read_b128 v[142:145], v42 offset:52288
	ds_read_b128 v[178:181], v42 offset:56640
	ds_read_b128 v[230:233], v41 offset:17536
	ds_read_b128 v[146:149], v42 offset:52352
	ds_read_b128 v[182:185], v42 offset:56704
	ds_read_b128 v[234:237], v41 offset:17600
	ds_read_b128 v[170:173], v42 offset:52416
	ds_read_b128 v[18:21], v42 offset:56768
	s_waitcnt lgkmcnt(9)
	v_mfma_f32_16x16x32_bf16 v[14:17], v[238:241], v[222:225], v[14:17]
	v_mfma_f32_16x16x32_bf16 v[10:13], v[174:177], v[222:225], v[10:13]
	s_waitcnt lgkmcnt(6)
	v_mfma_f32_16x16x32_bf16 v[14:17], v[142:145], v[226:229], v[14:17]
	v_mfma_f32_16x16x32_bf16 v[10:13], v[178:181], v[226:229], v[10:13]
	s_waitcnt lgkmcnt(3)
	v_mfma_f32_16x16x32_bf16 v[14:17], v[146:149], v[230:233], v[14:17]
	v_mfma_f32_16x16x32_bf16 v[10:13], v[182:185], v[230:233], v[10:13]
	s_waitcnt lgkmcnt(0)
	v_mfma_f32_16x16x32_bf16 v[14:17], v[170:173], v[234:237], v[14:17]
	v_mfma_f32_16x16x32_bf16 v[10:13], v[18:21], v[234:237], v[10:13]
	s_waitcnt vmcnt(20)
	ds_write_b128 v40, v[46:49]
	ds_write_b128 v40, v[50:53] offset:128
	ds_write_b128 v40, v[54:57] offset:34816
	ds_write_b128 v40, v[58:61] offset:34944
	s_waitcnt lgkmcnt(0)
	s_barrier
	ds_read_b128 v[222:225], v41
	ds_read_b128 v[238:241], v42 offset:34816
	ds_read_b128 v[174:177], v42 offset:39168
	ds_read_b128 v[226:229], v41 offset:64
	ds_read_b128 v[142:145], v42 offset:34880
	ds_read_b128 v[178:181], v42 offset:39232
	ds_read_b128 v[230:233], v41 offset:128
	ds_read_b128 v[146:149], v42 offset:34944
	ds_read_b128 v[182:185], v42 offset:39296
	ds_read_b128 v[234:237], v41 offset:192
	ds_read_b128 v[170:173], v42 offset:35008
	ds_read_b128 v[18:21], v42 offset:39360
	s_waitcnt lgkmcnt(9)
	v_mfma_f32_16x16x32_bf16 v[14:17], v[238:241], v[222:225], v[14:17]
	v_mfma_f32_16x16x32_bf16 v[10:13], v[174:177], v[222:225], v[10:13]
	s_waitcnt lgkmcnt(6)
	v_mfma_f32_16x16x32_bf16 v[14:17], v[142:145], v[226:229], v[14:17]
	v_mfma_f32_16x16x32_bf16 v[10:13], v[178:181], v[226:229], v[10:13]
	s_waitcnt lgkmcnt(3)
	v_mfma_f32_16x16x32_bf16 v[14:17], v[146:149], v[230:233], v[14:17]
	v_mfma_f32_16x16x32_bf16 v[10:13], v[182:185], v[230:233], v[10:13]
	s_waitcnt lgkmcnt(0)
	v_mfma_f32_16x16x32_bf16 v[14:17], v[170:173], v[234:237], v[14:17]
	v_mfma_f32_16x16x32_bf16 v[10:13], v[18:21], v[234:237], v[10:13]
	s_waitcnt vmcnt(16)
	ds_write_b128 v40, v[62:65] offset:17408
	ds_write_b128 v40, v[66:69] offset:17536
	ds_write_b128 v40, v[70:73] offset:52224
	ds_write_b128 v40, v[74:77] offset:52352
	s_waitcnt lgkmcnt(0)
	s_barrier
	ds_read_b128 v[222:225], v41 offset:17408
	ds_read_b128 v[238:241], v42 offset:52224
	ds_read_b128 v[174:177], v42 offset:56576
	ds_read_b128 v[226:229], v41 offset:17472
	ds_read_b128 v[142:145], v42 offset:52288
	ds_read_b128 v[178:181], v42 offset:56640
	ds_read_b128 v[230:233], v41 offset:17536
	ds_read_b128 v[146:149], v42 offset:52352
	ds_read_b128 v[182:185], v42 offset:56704
	ds_read_b128 v[234:237], v41 offset:17600
	ds_read_b128 v[170:173], v42 offset:52416
	ds_read_b128 v[18:21], v42 offset:56768
	s_waitcnt lgkmcnt(9)
	v_mfma_f32_16x16x32_bf16 v[14:17], v[238:241], v[222:225], v[14:17]
	v_mfma_f32_16x16x32_bf16 v[10:13], v[174:177], v[222:225], v[10:13]
	s_waitcnt lgkmcnt(6)
	v_mfma_f32_16x16x32_bf16 v[14:17], v[142:145], v[226:229], v[14:17]
	v_mfma_f32_16x16x32_bf16 v[10:13], v[178:181], v[226:229], v[10:13]
	s_waitcnt lgkmcnt(3)
	v_mfma_f32_16x16x32_bf16 v[14:17], v[146:149], v[230:233], v[14:17]
	v_mfma_f32_16x16x32_bf16 v[10:13], v[182:185], v[230:233], v[10:13]
	s_waitcnt lgkmcnt(0)
	v_mfma_f32_16x16x32_bf16 v[14:17], v[170:173], v[234:237], v[14:17]
	v_mfma_f32_16x16x32_bf16 v[10:13], v[18:21], v[234:237], v[10:13]
	s_waitcnt vmcnt(12)
	ds_write_b128 v40, v[78:81]
	ds_write_b128 v40, v[82:85] offset:128
	ds_write_b128 v40, v[86:89] offset:34816
	ds_write_b128 v40, v[90:93] offset:34944
	s_waitcnt lgkmcnt(0)
	s_barrier
; #define LDSBAR() do { asm volatile("s_waitcnt lgkmcnt(0)" ::: "memory"); __builtin_amdgcn_s_barrier(); asm volatile("" ::: "memory"); } while (0)
; #define SG_LOAD(R, s_) do { if ((s_) < ns) { R.a0 = NTL((const GAS v4u*)(ap + (s_) * 128)); R.a1 = NTL((const GAS v4u*)(ap + (s_) * 128 + 64)); R.b0 = NTL((const GAS v4u*)(bp + (s_) * 128)); R.b1 = NTL((const GAS v4u*)(bp + (s_) * 128 + 64)); } } while (0)
; #define SG_STORE(R, b_) do { *(LAS v4u*)(As + (b_) * BUF + prow * LDT + pk) = R.a0; *(LAS v4u*)(As + (b_) * BUF + prow * LDT + pk + 64) = R.a1; *(LAS v4u*)(Bs + (b_) * BUF + prow * LDT + pk) = R.b0; *(LAS v4u*)(Bs + (b_) * BUF + prow * LDT + pk + 64) = R.b1; } while (0)
; template <class Epi>
; __device__ __forceinline__ void small_gemm(const Frame& F, const bf16* A, const bf16* Bt, int row_base, int K, const Epi E) {
;     ...
;         SgPre R0, R1, R2, R3;
;         SG_LOAD(R0, 0); SG_LOAD(R1, 1); SG_LOAD(R2, 2);
;         SG_STORE(R0, 0); LDSBAR();
;         for (int s = 0; s < ns; s += 4) {
;             SG_LOAD(R3, s + 3); SG_COMP(0); if (s + 1 < ns) SG_STORE(R1, 1); LDSBAR(); if (s + 1 >= ns) break;
;             SG_LOAD(R0, s + 4); SG_COMP(1); if (s + 2 < ns) SG_STORE(R2, 0); LDSBAR(); if (s + 2 >= ns) break;
;             SG_LOAD(R1, s + 5); SG_COMP(0); if (s + 3 < ns) SG_STORE(R3, 1); LDSBAR(); if (s + 3 >= ns) break;
;             SG_LOAD(R2, s + 6); SG_COMP(1); if (s + 4 < ns) SG_STORE(R0, 0); LDSBAR();
;         }
;     ...
;         { float ss = E.store4p(r0 + 16 * (w & 3) + r, c0 + 32 * (w >> 2) + 4 * q, acc0, ep0);
;           ss += E.store4p(r0 + 16 * (w & 3) + r, c0 + 32 * (w >> 2) + 16 + 4 * q, acc1, ep1);
	ds_read_b128 v[222:225], v41
	ds_read_b128 v[238:241], v42 offset:34816
	ds_read_b128 v[174:177], v42 offset:39168
	ds_read_b128 v[226:229], v41 offset:64
	ds_read_b128 v[142:145], v42 offset:34880
	ds_read_b128 v[178:181], v42 offset:39232
	ds_read_b128 v[230:233], v41 offset:128
	ds_read_b128 v[146:149], v42 offset:34944
	ds_read_b128 v[182:185], v42 offset:39296
	ds_read_b128 v[234:237], v41 offset:192
	ds_read_b128 v[170:173], v42 offset:35008
	ds_read_b128 v[18:21], v42 offset:39360
	s_waitcnt lgkmcnt(9)
	v_mfma_f32_16x16x32_bf16 v[14:17], v[238:241], v[222:225], v[14:17]
	v_mfma_f32_16x16x32_bf16 v[10:13], v[174:177], v[222:225], v[10:13]
	s_waitcnt lgkmcnt(6)
	v_mfma_f32_16x16x32_bf16 v[14:17], v[142:145], v[226:229], v[14:17]
	v_mfma_f32_16x16x32_bf16 v[10:13], v[178:181], v[226:229], v[10:13]
	s_waitcnt lgkmcnt(3)
	v_mfma_f32_16x16x32_bf16 v[14:17], v[146:149], v[230:233], v[14:17]
	v_mfma_f32_16x16x32_bf16 v[10:13], v[182:185], v[230:233], v[10:13]
	s_waitcnt lgkmcnt(0)
	v_mfma_f32_16x16x32_bf16 v[14:17], v[170:173], v[234:237], v[14:17]
	v_mfma_f32_16x16x32_bf16 v[10:13], v[18:21], v[234:237], v[10:13]
	s_waitcnt vmcnt(8)
	ds_write_b128 v40, v[94:97] offset:17408
	ds_write_b128 v40, v[98:101] offset:17536
	ds_write_b128 v40, v[102:105] offset:52224
	ds_write_b128 v40, v[106:109] offset:52352
	s_waitcnt lgkmcnt(0)
	s_barrier
	ds_read_b128 v[222:225], v41 offset:17408
	ds_read_b128 v[238:241], v42 offset:52224
	ds_read_b128 v[174:177], v42 offset:56576
	ds_read_b128 v[226:229], v41 offset:17472
	ds_read_b128 v[142:145], v42 offset:52288
	ds_read_b128 v[178:181], v42 offset:56640
	ds_read_b128 v[230:233], v41 offset:17536
	ds_read_b128 v[146:149], v42 offset:52352
	ds_read_b128 v[182:185], v42 offset:56704
	ds_read_b128 v[234:237], v41 offset:17600
	ds_read_b128 v[170:173], v42 offset:52416
	ds_read_b128 v[18:21], v42 offset:56768
	s_waitcnt lgkmcnt(9)
	v_mfma_f32_16x16x32_bf16 v[14:17], v[238:241], v[222:225], v[14:17]
	v_mfma_f32_16x16x32_bf16 v[10:13], v[174:177], v[222:225], v[10:13]
	s_waitcnt lgkmcnt(6)
	v_mfma_f32_16x16x32_bf16 v[14:17], v[142:145], v[226:229], v[14:17]
	v_mfma_f32_16x16x32_bf16 v[10:13], v[178:181], v[226:229], v[10:13]
	s_waitcnt lgkmcnt(3)
	v_mfma_f32_16x16x32_bf16 v[14:17], v[146:149], v[230:233], v[14:17]
	v_mfma_f32_16x16x32_bf16 v[10:13], v[182:185], v[230:233], v[10:13]
	s_waitcnt lgkmcnt(0)
	v_mfma_f32_16x16x32_bf16 v[14:17], v[170:173], v[234:237], v[14:17]
	v_mfma_f32_16x16x32_bf16 v[10:13], v[18:21], v[234:237], v[10:13]
	s_waitcnt vmcnt(4)
	ds_write_b128 v40, v[110:113]
	ds_write_b128 v40, v[114:117] offset:128
	ds_write_b128 v40, v[118:121] offset:34816
	ds_write_b128 v40, v[122:125] offset:34944
	s_waitcnt lgkmcnt(0)
	s_barrier
	ds_read_b128 v[222:225], v41
	ds_read_b128 v[238:241], v42 offset:34816
	ds_read_b128 v[174:177], v42 offset:39168
	ds_read_b128 v[226:229], v41 offset:64
	ds_read_b128 v[142:145], v42 offset:34880
	ds_read_b128 v[178:181], v42 offset:39232
	ds_read_b128 v[230:233], v41 offset:128
	ds_read_b128 v[146:149], v42 offset:34944
	ds_read_b128 v[182:185], v42 offset:39296
	ds_read_b128 v[234:237], v41 offset:192
	ds_read_b128 v[170:173], v42 offset:35008
	ds_read_b128 v[18:21], v42 offset:39360
	s_waitcnt lgkmcnt(9)
	v_mfma_f32_16x16x32_bf16 v[14:17], v[238:241], v[222:225], v[14:17]
	v_mfma_f32_16x16x32_bf16 v[10:13], v[174:177], v[222:225], v[10:13]
	s_waitcnt lgkmcnt(6)
	v_mfma_f32_16x16x32_bf16 v[14:17], v[142:145], v[226:229], v[14:17]
	v_mfma_f32_16x16x32_bf16 v[10:13], v[178:181], v[226:229], v[10:13]
	s_waitcnt lgkmcnt(3)
	v_mfma_f32_16x16x32_bf16 v[14:17], v[146:149], v[230:233], v[14:17]
	v_mfma_f32_16x16x32_bf16 v[10:13], v[182:185], v[230:233], v[10:13]
	s_waitcnt lgkmcnt(0)
	v_mfma_f32_16x16x32_bf16 v[14:17], v[170:173], v[234:237], v[14:17]
	v_mfma_f32_16x16x32_bf16 v[10:13], v[18:21], v[234:237], v[10:13]
	s_waitcnt vmcnt(0)
	ds_write_b128 v40, v[126:129] offset:17408
	ds_write_b128 v40, v[130:133] offset:17536
	ds_write_b128 v40, v[134:137] offset:52224
	ds_write_b128 v40, v[138:141] offset:52352
	s_waitcnt lgkmcnt(0)
	s_barrier
	ds_read_b128 v[222:225], v41 offset:17408
	ds_read_b128 v[238:241], v42 offset:52224
	ds_read_b128 v[174:177], v42 offset:56576
	ds_read_b128 v[226:229], v41 offset:17472
	ds_read_b128 v[142:145], v42 offset:52288
	ds_read_b128 v[178:181], v42 offset:56640
	ds_read_b128 v[230:233], v41 offset:17536
	ds_read_b128 v[146:149], v42 offset:52352
	ds_read_b128 v[182:185], v42 offset:56704
	ds_read_b128 v[234:237], v41 offset:17600
	ds_read_b128 v[170:173], v42 offset:52416
	ds_read_b128 v[18:21], v42 offset:56768
	s_waitcnt lgkmcnt(9)
	v_mfma_f32_16x16x32_bf16 v[14:17], v[238:241], v[222:225], v[14:17]
	v_mfma_f32_16x16x32_bf16 v[10:13], v[174:177], v[222:225], v[10:13]
	s_waitcnt lgkmcnt(6)
	v_mfma_f32_16x16x32_bf16 v[14:17], v[142:145], v[226:229], v[14:17]
	v_mfma_f32_16x16x32_bf16 v[10:13], v[178:181], v[226:229], v[10:13]
	s_waitcnt lgkmcnt(3)
	v_mfma_f32_16x16x32_bf16 v[14:17], v[146:149], v[230:233], v[14:17]
	v_mfma_f32_16x16x32_bf16 v[10:13], v[182:185], v[230:233], v[10:13]
	s_waitcnt lgkmcnt(0)
	v_mfma_f32_16x16x32_bf16 v[14:17], v[170:173], v[234:237], v[14:17]
	v_mfma_f32_16x16x32_bf16 v[10:13], v[18:21], v[234:237], v[10:13]
	s_barrier
	s_nop 6
	v_fma_f32 v8, v16, 0.5, v8
	v_fma_f32 v9, v17, 0.5, v9
	v_pk_fma_f32 v[6:7], v[14:15], 0.5, v[6:7] op_sel_hi:[1,0,1]
	v_pk_fma_f32 v[4:5], v[12:13], 0.5, v[4:5] op_sel_hi:[1,0,1]
	v_pk_fma_f32 v[2:3], v[10:11], 0.5, v[2:3] op_sel_hi:[1,0,1]
	global_store_dwordx4 v[30:31], v[6:9], off
	global_store_dwordx4 v[30:31], v[2:5], off offset:64
	s_cbranch_scc1 .LBB0_1937
